# O1 / Q-up / KV-up k-loops: the 3rd/4th A and B fragments of the first k sub-step are requested at the barrier release into idle registers instead of right before their MFMAs; counted lgkmcnt waits rec
# baseline (speedup 1.0000x reference)
; __device__ __forceinline__ void rem_tile(int pos, int& mt, int& nt) { if (pos < 65) { mt = pos; nt = 40; } else { mt = 64; nt = pos - 65; } }
;     ...
;     auto issue = [&](u32x4 (&ra)[4], u32x4 (&rb)[2], u32x4& rx) {
;       const int idc = l_id < last_id ? l_id : last_id;
;       int mt, nt; if (TMAP == 1) rem_tile(idc, mt, nt); else tile_of(idc, ntn, mt, nt);
;       const bf16_t* A = (l_kt < ktsplit) ? A0 : A1;
;       const int kk = (l_kt < ktsplit) ? l_kt : l_kt - ktsplit;
;       const int arow = mt * 2 * BMH + hh * BMH + srow;
;     ...
;     auto compute = [&](int buf) {
;       const unsigned char* Ab = As + buf * ASTG + (wn * 64 + lr) * 128;
;       const unsigned char* Ax = Ax0 + buf * 128;
;       const unsigned char* Bb = Bs + buf * 16384 + (wm * 64 + lr) * 128;
; #pragma unroll
;       for (int ks = 0; ks < 2; ++ks) {
;         if (TI == 5 && ks == 1) __builtin_amdgcn_sched_barrier(0);
;         const int sw = ((ks * 4 + lq) ^ (lr & 7)) << 4;
;         bf16x8 wf[4], xf[TI];
; #pragma unroll
;         for (int i = 0; i < 4; ++i) {
;           wf[i] = *(const bf16x8*)(Bb + i * 2048 + sw);
;           xf[i] = *(const bf16x8*)(Ab + i * 2048 + sw);
;         }
.LBB0_589:
	v_add_u32_e32 v125, v143, v144
	ds_read_b128 v[30:33], v125 offset:32768
	v_add_u32_e32 v130, v142, v144
	ds_read_b128 v[34:37], v130
	ds_read_b128 v[38:41], v125 offset:34816
	ds_read_b128 v[42:45], v130 offset:2048
	ds_read_b128 v[242:245], v130 offset:4096
	ds_read_b128 v[246:249], v130 offset:6144
	ds_read_b128 v[250:253], v125 offset:36864
	ds_read_b128 v[214:217], v125 offset:38912
	s_min_i32 s11, s7, s31
	s_cmpk_gt_i32 s11, 0x3bf
	s_mov_b64 s[4:5], -1
	s_cbranch_scc0 .LBB0_591
	s_add_i32 s10, s11, 0xfffffc40
	s_mov_b64 s[4:5], 0

; #define MFMA16(a, b, c) __builtin_amdgcn_mfma_f32_16x16x32_bf16((a), (b), (c), 0, 0, 0)
;     ...
;     auto issue = [&](u32x4 (&ra)[4], u32x4 (&rb)[2], u32x4& rx) {
;       const int idc = l_id < last_id ? l_id : last_id;
;       int mt, nt; if (TMAP == 1) rem_tile(idc, mt, nt); else tile_of(idc, ntn, mt, nt);
;       const bf16_t* A = (l_kt < ktsplit) ? A0 : A1;
;       const int kk = (l_kt < ktsplit) ? l_kt : l_kt - ktsplit;
;       const int arow = mt * 2 * BMH + hh * BMH + srow;
;       const bf16_t* akb = A + kk * kstride + (tid & 7) * 8;
;       const bf16_t* wp = W + (size_t)(nt * 128 + wrow) * K + l_kt * 64 + (tid5 & 7) * 8;
; #pragma unroll
;       for (int i = 0; i < 4; ++i) {
;         int r = arow + 32 * i; r = r < M_ ? r : M_ - 1;
;         ra[i] = *(const u32x4*)(akb + (size_t)r * lda);
;       }
; #pragma unroll
;       for (int i = 0; i < 2; ++i) rb[i] = *(const u32x4*)(wp + (size_t)i * 64 * K);
;       if (TI == 5) rx = *(const u32x4*)(akb + (size_t)(arow - srow + 128) * lda);
;       if (++l_kt == nk) { l_kt = 0; l_id += G; }
;     };
;     ...
;     auto compute = [&](int buf) {
;       const unsigned char* Ab = As + buf * ASTG + (wn * 64 + lr) * 128;
;       const unsigned char* Ax = Ax0 + buf * 128;
;       const unsigned char* Bb = Bs + buf * 16384 + (wm * 64 + lr) * 128;
; #pragma unroll
;       for (int ks = 0; ks < 2; ++ks) {
;         if (TI == 5 && ks == 1) __builtin_amdgcn_sched_barrier(0);
;         const int sw = ((ks * 4 + lq) ^ (lr & 7)) << 4;
;         bf16x8 wf[4], xf[TI];
; #pragma unroll
;         for (int i = 0; i < 4; ++i) {
;           wf[i] = *(const bf16x8*)(Bb + i * 2048 + sw);
;           xf[i] = *(const bf16x8*)(Ab + i * 2048 + sw);
;         }
;         if (TI == 5) xf[TI - 1] = *(const bf16x8*)(Ax + ((ks * 4 + lq) << 4));
; #pragma unroll
;         for (int ni = 0; ni < 4; ++ni)
; #pragma unroll
;           for (int ti = 0; ti < 4; ++ti) acc[ni][ti] = MFMA16(wf[ni], xf[ti], acc[ni][ti]);
;         if (TI == 5) {
;           if (wn == 0) { acc[0][TI - 1] = MFMA16(wf[0], xf[TI - 1], acc[0][TI - 1]); acc[1][TI - 1] = MFMA16(wf[1], xf[TI - 1], acc[1][TI - 1]); }
;           else { acc[2][TI - 1] = MFMA16(wf[2], xf[TI - 1], acc[2][TI - 1]); acc[3][TI - 1] = MFMA16(wf[3], xf[TI - 1], acc[3][TI - 1]); }
;         }
;       }
;     };
.LBB0_593:
	s_cmp_lt_i32 s6, 2.0
	s_waitcnt lgkmcnt(5)
	v_mfma_f32_16x16x32_bf16 v[94:97], v[38:41], v[34:37], v[94:97]
	s_cselect_b32 s11, s43, 0
	s_cselect_b32 s12, s42, 0
	v_add_u32_e32 v117, s4, v139
	v_mfma_f32_16x16x32_bf16 v[50:53], v[30:33], v[34:37], v[110:113]
	s_lshl_b32 s4, s6, 6
	s_ashr_i32 s5, s4, 31
	s_lshl_b64 s[4:5], s[4:5], 1
	s_waitcnt lgkmcnt(4)
	v_mfma_f32_16x16x32_bf16 v[54:57], v[30:33], v[42:45], v[106:109]
	s_nop 2
	v_add_u32_e32 v13, v143, v145
	s_add_u32 s12, s12, s4
	s_waitcnt lgkmcnt(3)
	v_mfma_f32_16x16x32_bf16 v[102:105], v[30:33], v[242:245], v[102:105]
	s_addc_u32 s13, s11, s5
	v_mov_b32_e32 v115, v12
	v_add_u32_e32 v131, v142, v145
	s_waitcnt lgkmcnt(2)
	v_mfma_f32_16x16x32_bf16 v[30:33], v[30:33], v[246:249], v[98:101]
	s_mov_b32 s2, 0x20000
	s_mov_b32 s3, 0x30000
	s_add_i32 s35, s9, 1
	v_mfma_f32_16x16x32_bf16 v[90:93], v[38:41], v[42:45], v[90:93]
	s_cmp_lg_u32 s35, 16
	v_mfma_f32_16x16x32_bf16 v[86:89], v[38:41], v[242:245], v[86:89]
	v_mfma_f32_16x16x32_bf16 v[82:85], v[38:41], v[246:249], v[82:85]
	s_waitcnt lgkmcnt(0)
	v_mfma_f32_16x16x32_bf16 v[158:161], v[214:217], v[34:37], v[62:65]
	s_nop 2
	ds_read_b128 v[62:65], v13 offset:32768
	v_mfma_f32_16x16x32_bf16 v[132:135], v[250:253], v[34:37], v[78:81]
	v_min_i32_e32 v34, 0x405f, v117
	v_ashrrev_i32_e32 v35, 31, v34
	v_lshlrev_b64 v[34:35], 11, v[34:35]
	v_mfma_f32_16x16x32_bf16 v[150:153], v[250:253], v[42:45], v[74:77]
	s_nop 2
	v_lshl_add_u64 v[74:75], s[12:13], 0, v[114:115]
	v_mfma_f32_16x16x32_bf16 v[154:157], v[250:253], v[242:245], v[70:73]
	v_lshl_add_u64 v[34:35], v[74:75], 0, v[34:35]
	v_add_co_u32_e32 v34, vcc, s82, v34
	s_nop 0
	v_min_i32_e32 v70, 0x407f, v117
	v_ashrrev_i32_e32 v71, 31, v70
	v_mfma_f32_16x16x32_bf16 v[98:101], v[250:253], v[246:249], v[66:69]
	v_addc_co_u32_e32 v35, vcc, 0, v35, vcc
	v_lshl_add_u32 v76, s10, 7, v138
	s_nop 0
	v_lshlrev_b64 v[66:67], 11, v[70:71]
	v_lshl_add_u64 v[66:67], v[74:75], 0, v[66:67]
	v_mfma_f32_16x16x32_bf16 v[168:171], v[214:217], v[42:45], v[58:61]
	v_ashrrev_i32_e32 v77, 31, v76
	v_mfma_f32_16x16x32_bf16 v[176:179], v[214:217], v[242:245], v[46:49]
	ds_read_b128 v[106:109], v131
	global_load_dwordx4 v[42:45], v[66:67], off
	s_nop 0
	global_load_dwordx4 v[34:37], v[34:35], off
	ds_read_b128 v[78:81], v13 offset:34816
	ds_read_b128 v[202:205], v131 offset:2048
	ds_read_b128 v[206:209], v131 offset:4096
	ds_read_b128 v[210:213], v131 offset:6144
	v_mfma_f32_16x16x32_bf16 v[180:183], v[214:217], v[246:249], v[26:29]
	v_min_i32_e32 v38, 0x403f, v117
	v_ashrrev_i32_e32 v39, 31, v38
	v_lshlrev_b64 v[38:39], 11, v[38:39]
	v_min_i32_e32 v40, 0x401f, v117
	v_lshl_add_u64 v[38:39], v[74:75], 0, v[38:39]
	v_ashrrev_i32_e32 v41, 31, v40
	s_waitcnt lgkmcnt(4)
	v_mfma_f32_16x16x32_bf16 v[26:29], v[62:65], v[106:109], v[50:53]
	v_add_co_u32_e32 v38, vcc, s2, v38
	v_mov_b32_e32 v117, v12
	s_waitcnt lgkmcnt(2)
	v_mfma_f32_16x16x32_bf16 v[46:49], v[62:65], v[202:205], v[54:57]
	v_lshlrev_b64 v[50:51], 11, v[76:77]
	v_addc_co_u32_e32 v39, vcc, 0, v39, vcc
	s_waitcnt lgkmcnt(1)
	v_mfma_f32_16x16x32_bf16 v[58:61], v[62:65], v[206:209], v[102:105]
	v_lshl_add_u64 v[50:51], s[44:45], 0, v[50:51]
	v_lshl_add_u64 v[50:51], v[50:51], 0, s[4:5]
	v_lshl_add_u64 v[50:51], v[50:51], 0, v[116:117]
	s_waitcnt lgkmcnt(0)
	v_mfma_f32_16x16x32_bf16 v[62:65], v[62:65], v[210:213], v[30:33]
	s_waitcnt vmcnt(7)
	v_and_b32_e32 v103, 0xffff0000, v4
	s_waitcnt vmcnt(6)
	v_and_b32_e32 v102, 0xffff0000, v0
	v_pk_mul_f32 v[136:137], v[102:103], v[102:103]
	v_lshlrev_b64 v[30:31], 11, v[40:41]
	v_lshl_add_u64 v[30:31], v[74:75], 0, v[30:31]
	v_add_co_u32_e32 v30, vcc, s3, v30
	v_mfma_f32_16x16x32_bf16 v[66:69], v[78:81], v[106:109], v[94:97]
	s_nop 0
	v_addc_co_u32_e32 v31, vcc, 0, v31, vcc
	v_add_co_u32_e32 v52, vcc, s2, v50
	global_load_dwordx4 v[38:41], v[38:39], off
	s_nop 0
	global_load_dwordx4 v[30:33], v[30:31], off
	v_addc_co_u32_e32 v53, vcc, 0, v51, vcc
	ds_read_b128 v[94:97], v13 offset:36864
	ds_read_b128 v[214:217], v13 offset:38912
	global_load_dwordx4 v[54:57], v[50:51], off
	s_nop 0
	global_load_dwordx4 v[50:53], v[52:53], off
	v_mfma_f32_16x16x32_bf16 v[70:73], v[78:81], v[202:205], v[90:93]
	ds_write_b128 v141, v[4:7] offset:16384
	ds_write_b128 v141, v[0:3] offset:20480
	s_waitcnt vmcnt(9)
;     ...
;     auto store = [&](const u32x4 (&ra)[4], const u32x4 (&rb)[2], const u32x4& rx, int buf) {
; #pragma unroll
;       for (int i = 0; i < 4; ++i) {
;         if (RS) ss[i] += sumsq8(__builtin_bit_cast(bf16x8, ra[i]));
;         *(u32x4*)(As + buf * ASTG + i * 4096 + soff) = ra[i];
;       }
; #pragma unroll
;       for (int i = 0; i < 2; ++i) *(u32x4*)(Bs + buf * 16384 + i * 8192 + woff) = rb[i];
;       if (TI == 5) {
;         if (RS) ss[4] += sumsq8(__builtin_bit_cast(bf16x8, rx));
;         if (srow == 0) *(u32x4*)(Ax0 + buf * 128 + ((tid & 7) << 4)) = rx;
;       }
;       if (RS) {
;         if (++st_kt == nk) {
;           st_kt = 0;
; #pragma unroll
;           for (int i = 0; i < TI; ++i) {
;             float t = ss[i];
;             t += __shfl_xor(t, 1); t += __shfl_xor(t, 2); t += __shfl_xor(t, 4);
;             if ((tid & 7) == 0 && i < 4) rsl[srow + 32 * i] = rsqrtf(t * invK + EPS_);
;             ss[i] = 0.f;
;           }
;         }
;       }
;     };
	ds_write_b128 v141, v[14:17] offset:24576
	v_mfma_f32_16x16x32_bf16 v[74:77], v[78:81], v[206:209], v[86:89]
	s_waitcnt vmcnt(8)
	ds_write_b128 v141, v[8:11] offset:28672
	s_waitcnt vmcnt(7)
	ds_write_b128 v140, v[22:25] offset:49152
	s_waitcnt vmcnt(6)
	ds_write_b128 v140, v[18:21] offset:57344
	v_mfma_f32_16x16x32_bf16 v[78:81], v[78:81], v[210:213], v[82:85]
	s_waitcnt lgkmcnt(7)
	v_mfma_f32_16x16x32_bf16 v[82:85], v[94:97], v[106:109], v[132:135]
	s_nop 2
	v_lshlrev_b32_e32 v135, 16, v4
	v_lshlrev_b32_e32 v134, 16, v0
	v_and_b32_e32 v133, 0xffff0000, v5
	v_mfma_f32_16x16x32_bf16 v[86:89], v[94:97], v[202:205], v[150:153]
	v_lshlrev_b32_e32 v5, 16, v5
	v_lshlrev_b32_e32 v4, 16, v1
	v_and_b32_e32 v132, 0xffff0000, v1
	v_mfma_f32_16x16x32_bf16 v[90:93], v[94:97], v[206:209], v[154:157]
	v_and_b32_e32 v1, 0xffff0000, v15
	v_and_b32_e32 v0, 0xffff0000, v9
	v_mfma_f32_16x16x32_bf16 v[110:113], v[94:97], v[210:213], v[98:101]
	v_fma_f32 v94, v134, v134, v136
	v_fma_f32 v95, v135, v135, v137
	v_pk_fma_f32 v[4:5], v[4:5], v[4:5], v[94:95]
	v_lshlrev_b32_e32 v95, 16, v6
	v_pk_fma_f32 v[4:5], v[132:133], v[132:133], v[4:5]
	v_lshlrev_b32_e32 v94, 16, v2
	v_pk_fma_f32 v[4:5], v[94:95], v[94:95], v[4:5]
	v_and_b32_e32 v99, 0xffff0000, v6
	v_and_b32_e32 v98, 0xffff0000, v2
	v_pk_fma_f32 v[4:5], v[98:99], v[98:99], v[4:5]
	v_lshlrev_b32_e32 v133, 16, v7
	v_lshlrev_b32_e32 v132, 16, v3
	v_pk_fma_f32 v[4:5], v[132:133], v[132:133], v[4:5]
	v_and_b32_e32 v7, 0xffff0000, v7
	v_and_b32_e32 v6, 0xffff0000, v3
	v_pk_fma_f32 v[4:5], v[6:7], v[6:7], v[4:5]
	v_lshlrev_b32_e32 v3, 16, v14
	v_pk_add_f32 v[128:129], v[128:129], v[4:5]
	v_and_b32_e32 v5, 0xffff0000, v14
	v_and_b32_e32 v4, 0xffff0000, v8
	v_lshlrev_b32_e32 v2, 16, v8
	v_pk_mul_f32 v[4:5], v[4:5], v[4:5]
	v_lshlrev_b32_e32 v7, 16, v15
	v_lshlrev_b32_e32 v6, 16, v9
	v_pk_fma_f32 v[2:3], v[2:3], v[2:3], v[4:5]
	s_waitcnt lgkmcnt(6)
	v_mfma_f32_16x16x32_bf16 v[102:105], v[214:217], v[106:109], v[158:161]
	v_fma_f32 v2, v6, v6, v2
	v_fma_f32 v3, v7, v7, v3
	v_pk_fma_f32 v[0:1], v[0:1], v[0:1], v[2:3]
	v_lshlrev_b32_e32 v3, 16, v16
	v_lshlrev_b32_e32 v2, 16, v10
	v_pk_fma_f32 v[0:1], v[2:3], v[2:3], v[0:1]
	v_and_b32_e32 v3, 0xffff0000, v16
	v_and_b32_e32 v2, 0xffff0000, v10
	v_mfma_f32_16x16x32_bf16 v[106:109], v[214:217], v[202:205], v[168:171]
	v_fma_f32 v0, v2, v2, v0
	v_fma_f32 v1, v3, v3, v1
	v_lshlrev_b32_e32 v3, 16, v17
	v_lshlrev_b32_e32 v2, 16, v11
	v_mfma_f32_16x16x32_bf16 v[94:97], v[214:217], v[206:209], v[176:179]
	v_fma_f32 v0, v2, v2, v0
	v_fma_f32 v1, v3, v3, v1
	v_and_b32_e32 v3, 0xffff0000, v17
	v_and_b32_e32 v2, 0xffff0000, v11
	v_mfma_f32_16x16x32_bf16 v[98:101], v[214:217], v[210:213], v[180:183]
	v_fma_f32 v0, v2, v2, v0
	v_fma_f32 v1, v3, v3, v1
	v_pk_add_f32 v[126:127], v[126:127], v[0:1]
	s_cbranch_scc1 .LBB0_603
	v_and_b32_e32 v1, 64, v191
	v_xor_b32_e32 v0, 1, v191
	v_add_u32_e32 v2, 64, v1
	v_cmp_lt_i32_e32 vcc, v0, v2
	v_xor_b32_e32 v1, 2, v191
	v_xor_b32_e32 v5, 4, v191
	v_cndmask_b32_e32 v0, v191, v0, vcc
	v_lshlrev_b32_e32 v0, 2, v0
	ds_bpermute_b32 v3, v0, v129
	v_cmp_lt_i32_e32 vcc, v1, v2
	s_waitcnt lgkmcnt(0)
	v_add_f32_e32 v3, v129, v3
	v_cndmask_b32_e32 v1, v191, v1, vcc
	v_lshlrev_b32_e32 v1, 2, v1
	ds_bpermute_b32 v4, v1, v3
	v_cmp_lt_i32_e32 vcc, v5, v2
	s_waitcnt lgkmcnt(0)
	v_add_f32_e32 v3, v3, v4
	v_cndmask_b32_e32 v2, v191, v5, vcc
	v_lshlrev_b32_e32 v2, 2, v2
	ds_bpermute_b32 v4, v2, v3
	s_and_saveexec_b64 s[4:5], s[38:39]
	s_cbranch_execz .LBB0_596
	s_waitcnt lgkmcnt(0)
	v_add_f32_e32 v3, v3, v4
	v_fmamk_f32 v3, v3, 0x3a800000, v187
	v_mul_f32_e32 v4, 0x4b800000, v3
	v_cmp_gt_f32_e32 vcc, s33, v3
	s_nop 1
	v_cndmask_b32_e32 v3, v3, v4, vcc
	v_rsq_f32_e32 v3, v3
	s_nop 0
	v_mul_f32_e32 v4, 0x45800000, v3
	v_cndmask_b32_e32 v3, v3, v4, vcc
	ds_write_b32 v146, v3

; __device__ __forceinline__ void rem_tile(int pos, int& mt, int& nt) { if (pos < 65) { mt = pos; nt = 40; } else { mt = 64; nt = pos - 65; } }
;     ...
;     auto issue = [&](u32x4 (&ra)[4], u32x4 (&rb)[2], u32x4& rx) {
;       const int idc = l_id < last_id ? l_id : last_id;
;       int mt, nt; if (TMAP == 1) rem_tile(idc, mt, nt); else tile_of(idc, ntn, mt, nt);
;       const bf16_t* A = (l_kt < ktsplit) ? A0 : A1;
;       const int kk = (l_kt < ktsplit) ? l_kt : l_kt - ktsplit;
;       const int arow = mt * 2 * BMH + hh * BMH + srow;
;     ...
; #pragma unroll 1
;     for (int s = 0; s < S; s += 2) {
;       issue(ra0, rb0, rx0);
;       compute(0);
;       store(ra1, rb1, rx1, 1);
;       __syncthreads();
;       issue(ra1, rb1, rx1);
.LBB0_603:
	s_add_i32 s10, s6, 1
	s_cmp_eq_u32 s10, 16
	s_cselect_b64 s[4:5], -1, 0
	s_and_b64 s[12:13], s[4:5], exec
	s_load_dwordx2 s[12:13], s[0:1], 0x110
	s_waitcnt lgkmcnt(0)
	s_barrier
	ds_read_b128 v[0:3], v125 offset:49152
	ds_read_b128 v[4:7], v130 offset:16384
	ds_read_b128 v[8:11], v125 offset:51200
	ds_read_b128 v[14:17], v130 offset:18432
	ds_read_b128 v[242:245], v130 offset:20480
	ds_read_b128 v[246:249], v130 offset:22528
	ds_read_b128 v[250:253], v125 offset:53248
	s_cselect_b32 s34, s12, 0
	s_add_i32 s34, s34, s7
	s_min_i32 s11, s34, s31
	s_cmpk_gt_i32 s11, 0x3bf
	s_mov_b64 s[6:7], -1
	s_cbranch_scc0 .LBB0_605
	s_add_i32 s9, s11, 0xfffffc40
	s_mov_b64 s[6:7], 0

; #define MFMA16(a, b, c) __builtin_amdgcn_mfma_f32_16x16x32_bf16((a), (b), (c), 0, 0, 0)
;     ...
;     auto issue = [&](u32x4 (&ra)[4], u32x4 (&rb)[2], u32x4& rx) {
;       const int idc = l_id < last_id ? l_id : last_id;
;       int mt, nt; if (TMAP == 1) rem_tile(idc, mt, nt); else tile_of(idc, ntn, mt, nt);
;       const bf16_t* A = (l_kt < ktsplit) ? A0 : A1;
;       const int kk = (l_kt < ktsplit) ? l_kt : l_kt - ktsplit;
;       const int arow = mt * 2 * BMH + hh * BMH + srow;
;       const bf16_t* akb = A + kk * kstride + (tid & 7) * 8;
;       const bf16_t* wp = W + (size_t)(nt * 128 + wrow) * K + l_kt * 64 + (tid5 & 7) * 8;
; #pragma unroll
;       for (int i = 0; i < 4; ++i) {
;         int r = arow + 32 * i; r = r < M_ ? r : M_ - 1;
;         ra[i] = *(const u32x4*)(akb + (size_t)r * lda);
;       }
; #pragma unroll
;       for (int i = 0; i < 2; ++i) rb[i] = *(const u32x4*)(wp + (size_t)i * 64 * K);
;       if (TI == 5) rx = *(const u32x4*)(akb + (size_t)(arow - srow + 128) * lda);
;       if (++l_kt == nk) { l_kt = 0; l_id += G; }
;     };
;     ...
;     auto compute = [&](int buf) {
;       const unsigned char* Ab = As + buf * ASTG + (wn * 64 + lr) * 128;
;       const unsigned char* Ax = Ax0 + buf * 128;
;       const unsigned char* Bb = Bs + buf * 16384 + (wm * 64 + lr) * 128;
; #pragma unroll
;       for (int ks = 0; ks < 2; ++ks) {
;         if (TI == 5 && ks == 1) __builtin_amdgcn_sched_barrier(0);
;         const int sw = ((ks * 4 + lq) ^ (lr & 7)) << 4;
;         bf16x8 wf[4], xf[TI];
; #pragma unroll
;         for (int i = 0; i < 4; ++i) {
;           wf[i] = *(const bf16x8*)(Bb + i * 2048 + sw);
;           xf[i] = *(const bf16x8*)(Ab + i * 2048 + sw);
;         }
;         if (TI == 5) xf[TI - 1] = *(const bf16x8*)(Ax + ((ks * 4 + lq) << 4));
; #pragma unroll
;         for (int ni = 0; ni < 4; ++ni)
; #pragma unroll
;           for (int ti = 0; ti < 4; ++ti) acc[ni][ti] = MFMA16(wf[ni], xf[ti], acc[ni][ti]);
;         if (TI == 5) {
;           if (wn == 0) { acc[0][TI - 1] = MFMA16(wf[0], xf[TI - 1], acc[0][TI - 1]); acc[1][TI - 1] = MFMA16(wf[1], xf[TI - 1], acc[1][TI - 1]); }
;           else { acc[2][TI - 1] = MFMA16(wf[2], xf[TI - 1], acc[2][TI - 1]); acc[3][TI - 1] = MFMA16(wf[3], xf[TI - 1], acc[3][TI - 1]); }
;         }
;       }
;     };
.LBB0_607:
	s_and_b64 s[4:5], s[4:5], exec
	s_cselect_b32 s36, 0, s10
	s_waitcnt lgkmcnt(5)
	v_mfma_f32_16x16x32_bf16 v[18:21], v[0:3], v[4:7], v[26:29]
	s_cmp_lt_i32 s36, 2.0
	s_cselect_b32 s7, s43, 0
	s_cselect_b32 s10, s42, 0
	s_waitcnt lgkmcnt(3)
	v_mfma_f32_16x16x32_bf16 v[22:25], v[0:3], v[14:17], v[46:49]
	s_nop 1
	s_lshl_b32 s4, s36, 6
	s_ashr_i32 s5, s4, 31
	s_waitcnt lgkmcnt(2)
	v_mfma_f32_16x16x32_bf16 v[58:61], v[0:3], v[242:245], v[58:61]
	s_lshl_b64 s[4:5], s[4:5], 1
	v_mov_b32_e32 v115, v12
	v_lshl_add_u32 v130, s9, 7, v138
	s_waitcnt lgkmcnt(1)
	v_mfma_f32_16x16x32_bf16 v[0:3], v[0:3], v[246:249], v[62:65]
	s_mov_b32 s3, 0x20000
	s_mov_b32 s2, 0x30000
	v_mov_b32_e32 v117, v12
	v_mfma_f32_16x16x32_bf16 v[62:65], v[8:11], v[4:7], v[66:69]
	v_mfma_f32_16x16x32_bf16 v[66:69], v[8:11], v[14:17], v[70:73]
	v_mfma_f32_16x16x32_bf16 v[70:73], v[8:11], v[242:245], v[74:77]
	v_mfma_f32_16x16x32_bf16 v[8:11], v[8:11], v[246:249], v[78:81]
	s_nop 1
	ds_read_b128 v[78:81], v125 offset:55296
	ds_read_b128 v[180:183], v131 offset:16384
	s_waitcnt lgkmcnt(2)
	v_mfma_f32_16x16x32_bf16 v[132:135], v[250:253], v[4:7], v[82:85]
	s_waitcnt lgkmcnt(1)
	v_mfma_f32_16x16x32_bf16 v[168:171], v[78:81], v[4:7], v[102:105]
	ds_read_b128 v[4:7], v13 offset:49152
	v_mfma_f32_16x16x32_bf16 v[150:153], v[250:253], v[14:17], v[86:89]
	v_mfma_f32_16x16x32_bf16 v[158:161], v[250:253], v[246:249], v[110:113]
	v_mfma_f32_16x16x32_bf16 v[176:179], v[78:81], v[14:17], v[106:109]
	v_mfma_f32_16x16x32_bf16 v[202:205], v[78:81], v[246:249], v[98:101]
	ds_read_b128 v[14:17], v13 offset:51200
	ds_read_b128 v[46:49], v131 offset:18432
	ds_read_b128 v[206:209], v131 offset:22528
	v_mfma_f32_16x16x32_bf16 v[154:157], v[250:253], v[242:245], v[90:93]
	v_add_u32_e32 v74, s6, v139
	s_add_u32 s6, s10, s4
	s_addc_u32 s7, s7, s5
	s_waitcnt lgkmcnt(1)
	v_mfma_f32_16x16x32_bf16 v[106:109], v[4:7], v[46:49], v[22:25]
	v_lshl_add_u64 v[136:137], s[6:7], 0, v[114:115]
	s_add_i32 s8, s8, 2
	s_cmp_lg_u32 s8, 16
	v_min_i32_e32 v22, 0x407f, v74
	v_ashrrev_i32_e32 v23, 31, v22
	s_waitcnt lgkmcnt(0)
	v_mfma_f32_16x16x32_bf16 v[98:101], v[4:7], v[206:209], v[0:3]
	s_nop 2
	v_min_i32_e32 v2, 0x405f, v74
	v_mfma_f32_16x16x32_bf16 v[110:113], v[4:7], v[180:183], v[18:21]
	v_lshlrev_b64 v[0:1], 11, v[22:23]
	v_ashrrev_i32_e32 v3, 31, v2
	ds_read_b128 v[22:25], v13 offset:53248
	ds_read_b128 v[18:21], v131 offset:20480
	v_lshlrev_b64 v[2:3], 11, v[2:3]
	v_lshl_add_u64 v[2:3], v[136:137], 0, v[2:3]
	v_add_co_u32_e32 v2, vcc, s82, v2
	v_lshl_add_u64 v[0:1], v[136:137], 0, v[0:1]
	s_nop 0
	v_addc_co_u32_e32 v3, vcc, 0, v3, vcc
	s_waitcnt lgkmcnt(0)
	v_mfma_f32_16x16x32_bf16 v[102:105], v[4:7], v[18:21], v[58:61]
	global_load_dwordx4 v[4:7], v[0:1], off
	s_nop 0
	global_load_dwordx4 v[0:3], v[2:3], off
	v_min_i32_e32 v58, 0x403f, v74
	ds_read_b128 v[210:213], v13 offset:55296
	v_ashrrev_i32_e32 v59, 31, v58
	v_mfma_f32_16x16x32_bf16 v[82:85], v[14:17], v[206:209], v[8:11]
	v_ashrrev_i32_e32 v131, 31, v130
	s_nop 1
	v_lshlrev_b64 v[8:9], 11, v[58:59]
	v_min_i32_e32 v10, 0x401f, v74
	v_lshl_add_u64 v[8:9], v[136:137], 0, v[8:9]
	v_ashrrev_i32_e32 v11, 31, v10
	v_mfma_f32_16x16x32_bf16 v[26:29], v[78:81], v[242:245], v[94:97]
	v_add_co_u32_e32 v8, vcc, s3, v8
	v_lshlrev_b64 v[10:11], 11, v[10:11]
	v_mfma_f32_16x16x32_bf16 v[90:93], v[14:17], v[46:49], v[66:69]
	v_addc_co_u32_e32 v9, vcc, 0, v9, vcc
	v_lshl_add_u64 v[10:11], v[136:137], 0, v[10:11]
	v_mfma_f32_16x16x32_bf16 v[86:89], v[14:17], v[18:21], v[70:73]
	v_add_co_u32_e32 v10, vcc, s2, v10
	s_mov_b32 s2, 0x20000
	v_mfma_f32_16x16x32_bf16 v[78:81], v[22:25], v[180:183], v[132:135]
	v_addc_co_u32_e32 v11, vcc, 0, v11, vcc
	v_mfma_f32_16x16x32_bf16 v[74:77], v[22:25], v[46:49], v[150:153]
	v_mfma_f32_16x16x32_bf16 v[70:73], v[22:25], v[18:21], v[154:157]
	v_mfma_f32_16x16x32_bf16 v[66:69], v[22:25], v[206:209], v[158:161]
	v_lshlrev_b64 v[22:23], 11, v[130:131]
	v_lshl_add_u64 v[22:23], s[44:45], 0, v[22:23]
	v_lshl_add_u64 v[22:23], v[22:23], 0, s[4:5]
	v_lshl_add_u64 v[22:23], v[22:23], 0, v[116:117]
	v_add_co_u32_e32 v130, vcc, s3, v22
	v_mfma_f32_16x16x32_bf16 v[94:97], v[14:17], v[180:183], v[62:65]
	global_load_dwordx4 v[14:17], v[8:9], off
	s_nop 0
	global_load_dwordx4 v[8:11], v[10:11], off
	v_addc_co_u32_e32 v131, vcc, 0, v23, vcc
	s_waitcnt lgkmcnt(0)
	v_mfma_f32_16x16x32_bf16 v[58:61], v[210:213], v[46:49], v[176:179]
	v_mfma_f32_16x16x32_bf16 v[46:49], v[210:213], v[18:21], v[26:29]
	global_load_dwordx4 v[22:25], v[22:23], off
	s_nop 0
	global_load_dwordx4 v[18:21], v[130:131], off
	v_mfma_f32_16x16x32_bf16 v[62:65], v[210:213], v[180:183], v[168:171]
	v_mfma_f32_16x16x32_bf16 v[26:29], v[210:213], v[206:209], v[202:205]
	s_cbranch_scc1 .LBB0_627
	ds_read2_b32 v[132:133], v148 offset1:16
	ds_read2_b32 v[130:131], v148 offset0:32 offset1:48
	s_cmpk_gt_i32 s30, 0x3bf
	s_mov_b64 s[4:5], -1
	s_cbranch_scc0 .LBB0_611
	s_add_i32 s8, s30, 0xfffffc40
	s_movk_i32 s4, 0x4000
	s_cbranch_execz .LBB0_612

; __device__ __forceinline__ void rem_tile(int pos, int& mt, int& nt) { if (pos < 65) { mt = pos; nt = 40; } else { mt = 64; nt = pos - 65; } }
;     ...
;     auto issue = [&](u32x4 (&ra)[4], u32x4 (&rb)[2], u32x4& rx) {
;       const int idc = l_id < last_id ? l_id : last_id;
;       int mt, nt; if (TMAP == 1) rem_tile(idc, mt, nt); else tile_of(idc, ntn, mt, nt);
;       const bf16_t* A = (l_kt < ktsplit) ? A0 : A1;
;       const int kk = (l_kt < ktsplit) ? l_kt : l_kt - ktsplit;
;       const int arow = mt * 2 * BMH + hh * BMH + srow;
;     ...
;     auto compute = [&](int buf) {
;       const unsigned char* Ab = As + buf * ASTG + (wn * 64 + lr) * 128;
;       const unsigned char* Ax = Ax0 + buf * 128;
;       const unsigned char* Bb = Bs + buf * 16384 + (wm * 64 + lr) * 128;
; #pragma unroll
;       for (int ks = 0; ks < 2; ++ks) {
;         if (TI == 5 && ks == 1) __builtin_amdgcn_sched_barrier(0);
;         const int sw = ((ks * 4 + lq) ^ (lr & 7)) << 4;
;         bf16x8 wf[4], xf[TI];
; #pragma unroll
;         for (int i = 0; i < 4; ++i) {
;           wf[i] = *(const bf16x8*)(Bb + i * 2048 + sw);
;           xf[i] = *(const bf16x8*)(Ab + i * 2048 + sw);
;         }
.LBB0_698:
	v_add_u32_e32 v119, v133, v134
	ds_read_b128 v[30:33], v119 offset:32768
	v_add_u32_e32 v124, v132, v134
	ds_read_b128 v[34:37], v124
	ds_read_b128 v[38:41], v119 offset:34816
	ds_read_b128 v[42:45], v124 offset:2048
	ds_read_b128 v[242:245], v124 offset:4096
	ds_read_b128 v[246:249], v124 offset:6144
	ds_read_b128 v[250:253], v119 offset:36864
	ds_read_b128 v[206:209], v119 offset:38912
	s_min_i32 s46, s11, s35
	s_cmpk_gt_i32 s46, 0x2ff
	s_mov_b64 s[12:13], -1
	s_cbranch_scc0 .LBB0_700
	s_add_i32 s44, s46, 0xfffffd00
	s_mov_b64 s[12:13], 0

; #define MFMA16(a, b, c) __builtin_amdgcn_mfma_f32_16x16x32_bf16((a), (b), (c), 0, 0, 0)
;     ...
;     auto issue = [&](u32x4 (&ra)[4], u32x4 (&rb)[2], u32x4& rx) {
;       const int idc = l_id < last_id ? l_id : last_id;
;       int mt, nt; if (TMAP == 1) rem_tile(idc, mt, nt); else tile_of(idc, ntn, mt, nt);
;       const bf16_t* A = (l_kt < ktsplit) ? A0 : A1;
;       const int kk = (l_kt < ktsplit) ? l_kt : l_kt - ktsplit;
;       const int arow = mt * 2 * BMH + hh * BMH + srow;
;       const bf16_t* akb = A + kk * kstride + (tid & 7) * 8;
;       const bf16_t* wp = W + (size_t)(nt * 128 + wrow) * K + l_kt * 64 + (tid5 & 7) * 8;
; #pragma unroll
;       for (int i = 0; i < 4; ++i) {
;         int r = arow + 32 * i; r = r < M_ ? r : M_ - 1;
;         ra[i] = *(const u32x4*)(akb + (size_t)r * lda);
;       }
; #pragma unroll
;       for (int i = 0; i < 2; ++i) rb[i] = *(const u32x4*)(wp + (size_t)i * 64 * K);
;       if (TI == 5) rx = *(const u32x4*)(akb + (size_t)(arow - srow + 128) * lda);
;       if (++l_kt == nk) { l_kt = 0; l_id += G; }
;     };
;     ...
;     auto compute = [&](int buf) {
;       const unsigned char* Ab = As + buf * ASTG + (wn * 64 + lr) * 128;
;       const unsigned char* Ax = Ax0 + buf * 128;
;       const unsigned char* Bb = Bs + buf * 16384 + (wm * 64 + lr) * 128;
; #pragma unroll
;       for (int ks = 0; ks < 2; ++ks) {
;         if (TI == 5 && ks == 1) __builtin_amdgcn_sched_barrier(0);
;         const int sw = ((ks * 4 + lq) ^ (lr & 7)) << 4;
;         bf16x8 wf[4], xf[TI];
; #pragma unroll
;         for (int i = 0; i < 4; ++i) {
;           wf[i] = *(const bf16x8*)(Bb + i * 2048 + sw);
;           xf[i] = *(const bf16x8*)(Ab + i * 2048 + sw);
;         }
;         if (TI == 5) xf[TI - 1] = *(const bf16x8*)(Ax + ((ks * 4 + lq) << 4));
; #pragma unroll
;         for (int ni = 0; ni < 4; ++ni)
; #pragma unroll
;           for (int ti = 0; ti < 4; ++ti) acc[ni][ti] = MFMA16(wf[ni], xf[ti], acc[ni][ti]);
;         if (TI == 5) {
;           if (wn == 0) { acc[0][TI - 1] = MFMA16(wf[0], xf[TI - 1], acc[0][TI - 1]); acc[1][TI - 1] = MFMA16(wf[1], xf[TI - 1], acc[1][TI - 1]); }
;           else { acc[2][TI - 1] = MFMA16(wf[2], xf[TI - 1], acc[2][TI - 1]); acc[3][TI - 1] = MFMA16(wf[3], xf[TI - 1], acc[3][TI - 1]); }
;         }
;       }
;     };
.LBB0_702:
	s_cmp_lt_i32 s10, 2.0
	s_waitcnt lgkmcnt(5)
	v_mfma_f32_16x16x32_bf16 v[94:97], v[38:41], v[34:37], v[94:97]
	s_cselect_b32 s47, s5, 0
	s_cselect_b32 s46, s4, 0
	v_add_u32_e32 v117, s12, v129
	v_mfma_f32_16x16x32_bf16 v[50:53], v[30:33], v[34:37], v[110:113]
	s_lshl_b32 s12, s10, 6
	s_ashr_i32 s13, s12, 31
	s_lshl_b64 s[12:13], s[12:13], 1
	s_waitcnt lgkmcnt(4)
	v_mfma_f32_16x16x32_bf16 v[54:57], v[30:33], v[42:45], v[106:109]
	s_nop 2
	v_add_u32_e32 v13, v133, v135
	s_add_u32 s46, s46, s12
	s_waitcnt lgkmcnt(3)
	v_mfma_f32_16x16x32_bf16 v[102:105], v[30:33], v[242:245], v[102:105]
	s_addc_u32 s47, s47, s13
	v_mov_b32_e32 v115, v12
	s_mov_b32 s3, 0x8000
	s_waitcnt lgkmcnt(2)
	v_mfma_f32_16x16x32_bf16 v[30:33], v[30:33], v[246:249], v[98:101]
	v_add_u32_e32 v125, v132, v135
	s_waitcnt vmcnt(5)
	v_and_b32_e32 v127, 0xffff0000, v5
	s_waitcnt vmcnt(4)
	v_and_b32_e32 v126, 0xffff0000, v1
	v_mfma_f32_16x16x32_bf16 v[90:93], v[38:41], v[42:45], v[90:93]
	v_mfma_f32_16x16x32_bf16 v[86:89], v[38:41], v[242:245], v[86:89]
	v_mfma_f32_16x16x32_bf16 v[82:85], v[38:41], v[246:249], v[82:85]
	s_waitcnt lgkmcnt(0)
	v_mfma_f32_16x16x32_bf16 v[152:155], v[206:209], v[34:37], v[62:65]
	s_nop 2
	ds_read_b128 v[62:65], v13 offset:32768
	v_mfma_f32_16x16x32_bf16 v[140:143], v[250:253], v[34:37], v[78:81]
	v_min_i32_e32 v34, 0x405f, v117
	v_ashrrev_i32_e32 v35, 31, v34
	v_lshlrev_b64 v[34:35], 10, v[34:35]
	v_mfma_f32_16x16x32_bf16 v[144:147], v[250:253], v[42:45], v[74:77]
	s_nop 2
	v_lshl_add_u64 v[74:75], s[46:47], 0, v[114:115]
	v_mfma_f32_16x16x32_bf16 v[148:151], v[250:253], v[242:245], v[70:73]
	v_lshl_add_u64 v[34:35], v[74:75], 0, v[34:35]
	v_add_co_u32_e32 v34, vcc, s3, v34
	s_nop 0
	v_min_i32_e32 v70, 0x407f, v117
	v_ashrrev_i32_e32 v71, 31, v70
	v_mfma_f32_16x16x32_bf16 v[98:101], v[250:253], v[246:249], v[66:69]
	v_addc_co_u32_e32 v35, vcc, 0, v35, vcc
	v_lshl_add_u32 v76, s44, 7, v128
	s_nop 0
	v_lshlrev_b64 v[66:67], 10, v[70:71]
	v_lshl_add_u64 v[66:67], v[74:75], 0, v[66:67]
	v_mfma_f32_16x16x32_bf16 v[156:159], v[206:209], v[42:45], v[58:61]
	v_ashrrev_i32_e32 v77, 31, v76
	s_mov_b32 s44, 0x10000
	s_mov_b32 s3, 0x18000
	v_mfma_f32_16x16x32_bf16 v[160:163], v[206:209], v[242:245], v[46:49]
	ds_read_b128 v[106:109], v125
	global_load_dwordx4 v[42:45], v[66:67], off
	s_nop 0
	global_load_dwordx4 v[34:37], v[34:35], off
	ds_read_b128 v[78:81], v13 offset:34816
	ds_read_b128 v[176:179], v125 offset:2048
	ds_read_b128 v[180:183], v125 offset:4096
	ds_read_b128 v[202:205], v125 offset:6144
	v_mfma_f32_16x16x32_bf16 v[168:171], v[206:209], v[246:249], v[26:29]
	v_min_i32_e32 v38, 0x403f, v117
	v_ashrrev_i32_e32 v39, 31, v38
	v_lshlrev_b64 v[38:39], 10, v[38:39]
	v_min_i32_e32 v40, 0x401f, v117
	v_lshl_add_u64 v[38:39], v[74:75], 0, v[38:39]
	v_ashrrev_i32_e32 v41, 31, v40
	s_waitcnt lgkmcnt(4)
	v_mfma_f32_16x16x32_bf16 v[26:29], v[62:65], v[106:109], v[50:53]
	v_add_co_u32_e32 v38, vcc, s44, v38
	v_mov_b32_e32 v117, v12
	s_waitcnt lgkmcnt(2)
	v_mfma_f32_16x16x32_bf16 v[46:49], v[62:65], v[176:179], v[54:57]
	v_lshlrev_b64 v[50:51], 10, v[76:77]
	v_addc_co_u32_e32 v39, vcc, 0, v39, vcc
	s_waitcnt lgkmcnt(1)
	v_mfma_f32_16x16x32_bf16 v[58:61], v[62:65], v[180:183], v[102:105]
	v_lshl_add_u64 v[50:51], s[6:7], 0, v[50:51]
	v_lshl_add_u64 v[50:51], v[50:51], 0, s[12:13]
	v_lshl_add_u64 v[50:51], v[50:51], 0, v[116:117]
	s_waitcnt lgkmcnt(0)
	v_mfma_f32_16x16x32_bf16 v[62:65], v[62:65], v[202:205], v[30:33]
	v_and_b32_e32 v103, 0xffff0000, v4
	v_and_b32_e32 v102, 0xffff0000, v0
	s_add_i32 s47, s45, 1
	v_lshlrev_b64 v[30:31], 10, v[40:41]
	v_lshl_add_u64 v[30:31], v[74:75], 0, v[30:31]
	v_add_co_u32_e32 v30, vcc, s3, v30
	v_mfma_f32_16x16x32_bf16 v[66:69], v[78:81], v[106:109], v[94:97]
	s_nop 0
	v_addc_co_u32_e32 v31, vcc, 0, v31, vcc
	v_add_co_u32_e32 v52, vcc, s44, v50
	global_load_dwordx4 v[38:41], v[38:39], off
	s_nop 0
	global_load_dwordx4 v[30:33], v[30:31], off
	v_addc_co_u32_e32 v53, vcc, 0, v51, vcc
	ds_read_b128 v[94:97], v13 offset:36864
	ds_read_b128 v[206:209], v13 offset:38912
	global_load_dwordx4 v[54:57], v[50:51], off
	s_nop 0
	global_load_dwordx4 v[50:53], v[52:53], off
	v_mfma_f32_16x16x32_bf16 v[70:73], v[78:81], v[176:179], v[90:93]
	ds_write_b128 v131, v[4:7] offset:16384
	v_lshlrev_b32_e32 v5, 16, v5
	ds_write_b128 v131, v[0:3] offset:20480
	v_mfma_f32_16x16x32_bf16 v[74:77], v[78:81], v[180:183], v[86:89]
	s_cmp_lg_u32 s47, 8
	s_waitcnt vmcnt(9)
; #define MFMA16(a, b, c) __builtin_amdgcn_mfma_f32_16x16x32_bf16((a), (b), (c), 0, 0, 0)
;     ...
;     auto store = [&](const u32x4 (&ra)[4], const u32x4 (&rb)[2], const u32x4& rx, int buf) {
; #pragma unroll
;       for (int i = 0; i < 4; ++i) {
;         if (RS) ss[i] += sumsq8(__builtin_bit_cast(bf16x8, ra[i]));
;         *(u32x4*)(As + buf * ASTG + i * 4096 + soff) = ra[i];
;       }
; #pragma unroll
;       for (int i = 0; i < 2; ++i) *(u32x4*)(Bs + buf * 16384 + i * 8192 + woff) = rb[i];
;       if (TI == 5) {
;         if (RS) ss[4] += sumsq8(__builtin_bit_cast(bf16x8, rx));
;         if (srow == 0) *(u32x4*)(Ax0 + buf * 128 + ((tid & 7) << 4)) = rx;
;       }
;       if (RS) {
;         if (++st_kt == nk) {
;           st_kt = 0;
; #pragma unroll
;           for (int i = 0; i < TI; ++i) {
;             float t = ss[i];
;             t += __shfl_xor(t, 1); t += __shfl_xor(t, 2); t += __shfl_xor(t, 4);
;             if ((tid & 7) == 0 && i < 4) rsl[srow + 32 * i] = rsqrtf(t * invK + EPS_);
;             ss[i] = 0.f;
;           }
;         }
;       }
;     };
;     auto compute = [&](int buf) {
;       const unsigned char* Ab = As + buf * ASTG + (wn * 64 + lr) * 128;
;       const unsigned char* Ax = Ax0 + buf * 128;
;       const unsigned char* Bb = Bs + buf * 16384 + (wm * 64 + lr) * 128;
; #pragma unroll
;       for (int ks = 0; ks < 2; ++ks) {
;         if (TI == 5 && ks == 1) __builtin_amdgcn_sched_barrier(0);
;         const int sw = ((ks * 4 + lq) ^ (lr & 7)) << 4;
;         bf16x8 wf[4], xf[TI];
; #pragma unroll
;         for (int i = 0; i < 4; ++i) {
;           wf[i] = *(const bf16x8*)(Bb + i * 2048 + sw);
;           xf[i] = *(const bf16x8*)(Ab + i * 2048 + sw);
;         }
;         if (TI == 5) xf[TI - 1] = *(const bf16x8*)(Ax + ((ks * 4 + lq) << 4));
; #pragma unroll
;         for (int ni = 0; ni < 4; ++ni)
; #pragma unroll
;           for (int ti = 0; ti < 4; ++ti) acc[ni][ti] = MFMA16(wf[ni], xf[ti], acc[ni][ti]);
;         if (TI == 5) {
;           if (wn == 0) { acc[0][TI - 1] = MFMA16(wf[0], xf[TI - 1], acc[0][TI - 1]); acc[1][TI - 1] = MFMA16(wf[1], xf[TI - 1], acc[1][TI - 1]); }
;           else { acc[2][TI - 1] = MFMA16(wf[2], xf[TI - 1], acc[2][TI - 1]); acc[3][TI - 1] = MFMA16(wf[3], xf[TI - 1], acc[3][TI - 1]); }
;         }
;       }
;     };
	ds_write_b128 v131, v[14:17] offset:24576
	s_waitcnt vmcnt(8)
	ds_write_b128 v131, v[8:11] offset:28672
	s_waitcnt vmcnt(7)
	ds_write_b128 v130, v[22:25] offset:49152
	v_mfma_f32_16x16x32_bf16 v[78:81], v[78:81], v[202:205], v[82:85]
	s_waitcnt vmcnt(6)
	ds_write_b128 v130, v[18:21] offset:57344
	s_waitcnt lgkmcnt(7)
	v_mfma_f32_16x16x32_bf16 v[82:85], v[94:97], v[106:109], v[140:143]
	s_nop 2
	v_lshlrev_b32_e32 v141, 16, v4
	v_lshlrev_b32_e32 v140, 16, v0
	v_pk_mul_f32 v[142:143], v[102:103], v[102:103]
	v_mfma_f32_16x16x32_bf16 v[86:89], v[94:97], v[176:179], v[144:147]
	v_lshlrev_b32_e32 v4, 16, v1
	v_and_b32_e32 v1, 0xffff0000, v15
	v_and_b32_e32 v0, 0xffff0000, v9
	v_mfma_f32_16x16x32_bf16 v[90:93], v[94:97], v[180:183], v[148:151]
	v_mfma_f32_16x16x32_bf16 v[110:113], v[94:97], v[202:205], v[98:101]
	v_fma_f32 v94, v140, v140, v142
	v_fma_f32 v95, v141, v141, v143
	v_pk_fma_f32 v[4:5], v[4:5], v[4:5], v[94:95]
	v_lshlrev_b32_e32 v95, 16, v6
	v_pk_fma_f32 v[4:5], v[126:127], v[126:127], v[4:5]
	v_lshlrev_b32_e32 v94, 16, v2
	v_pk_fma_f32 v[4:5], v[94:95], v[94:95], v[4:5]
	v_and_b32_e32 v99, 0xffff0000, v6
	v_and_b32_e32 v98, 0xffff0000, v2
	v_pk_fma_f32 v[4:5], v[98:99], v[98:99], v[4:5]
	v_lshlrev_b32_e32 v127, 16, v7
	v_lshlrev_b32_e32 v126, 16, v3
	v_pk_fma_f32 v[4:5], v[126:127], v[126:127], v[4:5]
	v_and_b32_e32 v7, 0xffff0000, v7
	v_and_b32_e32 v6, 0xffff0000, v3
	v_pk_fma_f32 v[4:5], v[6:7], v[6:7], v[4:5]
	v_lshlrev_b32_e32 v3, 16, v14
	v_pk_add_f32 v[122:123], v[122:123], v[4:5]
	v_and_b32_e32 v5, 0xffff0000, v14
	v_and_b32_e32 v4, 0xffff0000, v8
	v_lshlrev_b32_e32 v2, 16, v8
	v_pk_mul_f32 v[4:5], v[4:5], v[4:5]
	v_lshlrev_b32_e32 v7, 16, v15
	v_lshlrev_b32_e32 v6, 16, v9
	v_pk_fma_f32 v[2:3], v[2:3], v[2:3], v[4:5]
	s_waitcnt lgkmcnt(6)
	v_mfma_f32_16x16x32_bf16 v[102:105], v[206:209], v[106:109], v[152:155]
	v_fma_f32 v2, v6, v6, v2
	v_fma_f32 v3, v7, v7, v3
	v_pk_fma_f32 v[0:1], v[0:1], v[0:1], v[2:3]
	v_lshlrev_b32_e32 v3, 16, v16
	v_lshlrev_b32_e32 v2, 16, v10
	v_pk_fma_f32 v[0:1], v[2:3], v[2:3], v[0:1]
	v_and_b32_e32 v3, 0xffff0000, v16
	v_and_b32_e32 v2, 0xffff0000, v10
	v_mfma_f32_16x16x32_bf16 v[106:109], v[206:209], v[176:179], v[156:159]
	v_fma_f32 v0, v2, v2, v0
	v_fma_f32 v1, v3, v3, v1
	v_lshlrev_b32_e32 v3, 16, v17
	v_lshlrev_b32_e32 v2, 16, v11
	v_mfma_f32_16x16x32_bf16 v[94:97], v[206:209], v[180:183], v[160:163]
	v_fma_f32 v0, v2, v2, v0
	v_fma_f32 v1, v3, v3, v1
	v_and_b32_e32 v3, 0xffff0000, v17
	v_and_b32_e32 v2, 0xffff0000, v11
	v_mfma_f32_16x16x32_bf16 v[98:101], v[206:209], v[202:205], v[168:171]
	v_fma_f32 v0, v2, v2, v0
	v_fma_f32 v1, v3, v3, v1
	v_pk_add_f32 v[120:121], v[120:121], v[0:1]
	s_cbranch_scc1 .LBB0_712
	v_and_b32_e32 v1, 64, v191
	v_xor_b32_e32 v0, 1, v191
	v_add_u32_e32 v2, 64, v1
	v_cmp_lt_i32_e32 vcc, v0, v2
	v_xor_b32_e32 v1, 2, v191
	v_xor_b32_e32 v5, 4, v191
	v_cndmask_b32_e32 v0, v191, v0, vcc
	v_lshlrev_b32_e32 v0, 2, v0
	ds_bpermute_b32 v3, v0, v123
	v_cmp_lt_i32_e32 vcc, v1, v2
	s_waitcnt lgkmcnt(0)
	v_add_f32_e32 v3, v123, v3
	v_cndmask_b32_e32 v1, v191, v1, vcc
	v_lshlrev_b32_e32 v1, 2, v1
	ds_bpermute_b32 v4, v1, v3
	v_cmp_lt_i32_e32 vcc, v5, v2
	s_waitcnt lgkmcnt(0)
	v_add_f32_e32 v3, v3, v4
	v_cndmask_b32_e32 v2, v191, v5, vcc
	v_lshlrev_b32_e32 v2, 2, v2
	ds_bpermute_b32 v4, v2, v3
	s_and_saveexec_b64 s[12:13], s[38:39]
	s_cbranch_execz .LBB0_705
	s_waitcnt lgkmcnt(0)
	v_add_f32_e32 v3, v3, v4
	v_fmamk_f32 v3, v3, 0x3b000000, v187
	v_mul_f32_e32 v4, 0x4b800000, v3
	v_cmp_gt_f32_e32 vcc, s33, v3
	s_nop 1
	v_cndmask_b32_e32 v3, v3, v4, vcc
	v_rsq_f32_e32 v3, v3
	s_nop 0
	v_mul_f32_e32 v4, 0x45800000, v3
	v_cndmask_b32_e32 v3, v3, v4, vcc
	ds_write_b32 v136, v3

;     ...
;     auto compute = [&](int buf) {
;       const unsigned char* Ab = As + buf * ASTG + (wn * 64 + lr) * 128;
;       const unsigned char* Ax = Ax0 + buf * 128;
;       const unsigned char* Bb = Bs + buf * 16384 + (wm * 64 + lr) * 128;
; #pragma unroll
;       for (int ks = 0; ks < 2; ++ks) {
;         if (TI == 5 && ks == 1) __builtin_amdgcn_sched_barrier(0);
;         const int sw = ((ks * 4 + lq) ^ (lr & 7)) << 4;
;         bf16x8 wf[4], xf[TI];
; #pragma unroll
;         for (int i = 0; i < 4; ++i) {
;           wf[i] = *(const bf16x8*)(Bb + i * 2048 + sw);
;           xf[i] = *(const bf16x8*)(Ab + i * 2048 + sw);
;         }
;     ...
;     for (int s = 0; s < S; s += 2) {
;       issue(ra0, rb0, rx0);
;       compute(0);
;       store(ra1, rb1, rx1, 1);
;       __syncthreads();
;       issue(ra1, rb1, rx1);
;       compute(1);
;       c_kt += 2;
;       if (c_kt == nk) { c_kt = 0; tile_end(); }
;       store(ra0, rb0, rx0, 0);
;       __syncthreads();
.LBB0_712:
	s_add_i32 s49, s10, 1
	s_cmp_eq_u32 s49, 8
	s_cselect_b64 s[12:13], -1, 0
	s_and_b64 s[44:45], s[12:13], exec
	s_load_dwordx2 s[44:45], s[0:1], 0x110
	s_waitcnt lgkmcnt(0)
	s_barrier
	ds_read_b128 v[0:3], v119 offset:49152
	ds_read_b128 v[4:7], v124 offset:16384
	ds_read_b128 v[8:11], v119 offset:51200
	ds_read_b128 v[14:17], v124 offset:18432
	ds_read_b128 v[242:245], v124 offset:20480
	ds_read_b128 v[246:249], v124 offset:22528
	ds_read_b128 v[250:253], v119 offset:53248
	s_cselect_b32 s46, s44, 0
	s_add_i32 s46, s46, s11
	s_min_i32 s52, s46, s35
	s_cmpk_gt_i32 s52, 0x2ff
	s_mov_b64 s[44:45], -1
	s_cbranch_scc0 .LBB0_714
	s_add_i32 s10, s52, 0xfffffd00
	s_mov_b64 s[44:45], 0

; #define MFMA16(a, b, c) __builtin_amdgcn_mfma_f32_16x16x32_bf16((a), (b), (c), 0, 0, 0)
; __device__ __forceinline__ void rem_tile(int pos, int& mt, int& nt) { if (pos < 65) { mt = pos; nt = 40; } else { mt = 64; nt = pos - 65; } }
;     ...
;     auto issue = [&](u32x4 (&ra)[4], u32x4 (&rb)[2], u32x4& rx) {
;       const int idc = l_id < last_id ? l_id : last_id;
;       int mt, nt; if (TMAP == 1) rem_tile(idc, mt, nt); else tile_of(idc, ntn, mt, nt);
;       const bf16_t* A = (l_kt < ktsplit) ? A0 : A1;
;       const int kk = (l_kt < ktsplit) ? l_kt : l_kt - ktsplit;
;       const int arow = mt * 2 * BMH + hh * BMH + srow;
;       const bf16_t* akb = A + kk * kstride + (tid & 7) * 8;
;       const bf16_t* wp = W + (size_t)(nt * 128 + wrow) * K + l_kt * 64 + (tid5 & 7) * 8;
; #pragma unroll
;       for (int i = 0; i < 4; ++i) {
;         int r = arow + 32 * i; r = r < M_ ? r : M_ - 1;
;         ra[i] = *(const u32x4*)(akb + (size_t)r * lda);
;       }
; #pragma unroll
;       for (int i = 0; i < 2; ++i) rb[i] = *(const u32x4*)(wp + (size_t)i * 64 * K);
;     ...
;     auto compute = [&](int buf) {
;       const unsigned char* Ab = As + buf * ASTG + (wn * 64 + lr) * 128;
;       const unsigned char* Ax = Ax0 + buf * 128;
;       const unsigned char* Bb = Bs + buf * 16384 + (wm * 64 + lr) * 128;
; #pragma unroll
;       for (int ks = 0; ks < 2; ++ks) {
;         if (TI == 5 && ks == 1) __builtin_amdgcn_sched_barrier(0);
;         const int sw = ((ks * 4 + lq) ^ (lr & 7)) << 4;
;         bf16x8 wf[4], xf[TI];
; #pragma unroll
;         for (int i = 0; i < 4; ++i) {
;           wf[i] = *(const bf16x8*)(Bb + i * 2048 + sw);
;           xf[i] = *(const bf16x8*)(Ab + i * 2048 + sw);
;         }
;         if (TI == 5) xf[TI - 1] = *(const bf16x8*)(Ax + ((ks * 4 + lq) << 4));
; #pragma unroll
;         for (int ni = 0; ni < 4; ++ni)
; #pragma unroll
;           for (int ti = 0; ti < 4; ++ti) acc[ni][ti] = MFMA16(wf[ni], xf[ti], acc[ni][ti]);
;         if (TI == 5) {
;           if (wn == 0) { acc[0][TI - 1] = MFMA16(wf[0], xf[TI - 1], acc[0][TI - 1]); acc[1][TI - 1] = MFMA16(wf[1], xf[TI - 1], acc[1][TI - 1]); }
;           else { acc[2][TI - 1] = MFMA16(wf[2], xf[TI - 1], acc[2][TI - 1]); acc[3][TI - 1] = MFMA16(wf[3], xf[TI - 1], acc[3][TI - 1]); }
;         }
;       }
;     };
.LBB0_716:
	s_and_b64 s[12:13], s[12:13], exec
	s_cselect_b32 s44, 0, s49
	s_waitcnt lgkmcnt(5)
	v_mfma_f32_16x16x32_bf16 v[18:21], v[0:3], v[4:7], v[26:29]
	s_cmp_lt_i32 s44, 2.0
	s_cselect_b32 s45, s5, 0
	s_cselect_b32 s49, s4, 0
	s_waitcnt lgkmcnt(3)
	v_mfma_f32_16x16x32_bf16 v[22:25], v[0:3], v[14:17], v[46:49]
	s_nop 1
	s_lshl_b32 s12, s44, 6
	s_ashr_i32 s13, s12, 31
	s_waitcnt lgkmcnt(2)
	v_mfma_f32_16x16x32_bf16 v[58:61], v[0:3], v[242:245], v[58:61]
	s_lshl_b64 s[12:13], s[12:13], 1
	s_add_u32 s52, s49, s12
	s_addc_u32 s53, s45, s13
	s_waitcnt lgkmcnt(1)
	v_mfma_f32_16x16x32_bf16 v[0:3], v[0:3], v[246:249], v[62:65]
	v_mov_b32_e32 v115, v12
	v_lshl_add_u64 v[172:173], s[52:53], 0, v[114:115]
	s_mov_b32 s3, 0x8000
	v_mfma_f32_16x16x32_bf16 v[62:65], v[8:11], v[4:7], v[66:69]
	v_lshl_add_u32 v184, s10, 7, v128
	v_ashrrev_i32_e32 v185, 31, v184
	s_mov_b32 s10, 0x10000
	v_mfma_f32_16x16x32_bf16 v[66:69], v[8:11], v[14:17], v[70:73]
	v_mov_b32_e32 v117, v12
	s_add_i32 s37, s37, 2
	s_mov_b32 s82, 0x10000
	v_mfma_f32_16x16x32_bf16 v[70:73], v[8:11], v[242:245], v[74:77]
	s_cmp_lg_u32 s37, 8
	v_mfma_f32_16x16x32_bf16 v[8:11], v[8:11], v[246:249], v[78:81]
	s_nop 0
	s_nop 0
	ds_read_b128 v[78:81], v119 offset:55296
	ds_read_b128 v[168:171], v125 offset:16384
	s_waitcnt lgkmcnt(2)
	v_mfma_f32_16x16x32_bf16 v[140:143], v[250:253], v[4:7], v[82:85]
	s_waitcnt lgkmcnt(1)
	v_mfma_f32_16x16x32_bf16 v[156:159], v[78:81], v[4:7], v[102:105]
	ds_read_b128 v[4:7], v13 offset:49152
	v_mfma_f32_16x16x32_bf16 v[144:147], v[250:253], v[14:17], v[86:89]
	v_mfma_f32_16x16x32_bf16 v[152:155], v[250:253], v[246:249], v[110:113]
	v_mfma_f32_16x16x32_bf16 v[160:163], v[78:81], v[14:17], v[106:109]
	v_mfma_f32_16x16x32_bf16 v[176:179], v[78:81], v[246:249], v[98:101]
	ds_read_b128 v[14:17], v13 offset:51200
	ds_read_b128 v[46:49], v125 offset:18432
	s_waitcnt lgkmcnt(2)
	v_mfma_f32_16x16x32_bf16 v[110:113], v[4:7], v[168:171], v[18:21]
	s_nop 2
	ds_read_b128 v[18:21], v125 offset:20480
	ds_read_b128 v[124:127], v125 offset:22528
	v_mfma_f32_16x16x32_bf16 v[148:151], v[250:253], v[242:245], v[90:93]
	v_add_u32_e32 v74, s11, v129
	s_waitcnt lgkmcnt(2)
	v_mfma_f32_16x16x32_bf16 v[106:109], v[4:7], v[46:49], v[22:25]
	s_nop 2
	v_min_i32_e32 v22, 0x407f, v74
	v_ashrrev_i32_e32 v23, 31, v22
	s_waitcnt lgkmcnt(0)
	v_mfma_f32_16x16x32_bf16 v[98:101], v[4:7], v[124:127], v[0:3]
	s_nop 2
	v_min_i32_e32 v2, 0x405f, v74
	v_lshlrev_b64 v[0:1], 10, v[22:23]
	v_ashrrev_i32_e32 v3, 31, v2
	ds_read_b128 v[22:25], v13 offset:53248
	v_lshlrev_b64 v[2:3], 10, v[2:3]
	v_lshl_add_u64 v[2:3], v[172:173], 0, v[2:3]
	v_add_co_u32_e32 v2, vcc, s3, v2
	v_lshl_add_u64 v[0:1], v[172:173], 0, v[0:1]
	s_nop 0
	v_addc_co_u32_e32 v3, vcc, 0, v3, vcc
	v_mfma_f32_16x16x32_bf16 v[102:105], v[4:7], v[18:21], v[58:61]
	global_load_dwordx4 v[4:7], v[0:1], off
	s_nop 0
	global_load_dwordx4 v[0:3], v[2:3], off
	v_min_i32_e32 v58, 0x403f, v74
	ds_read_b128 v[180:183], v13 offset:55296
	v_ashrrev_i32_e32 v59, 31, v58
	v_mfma_f32_16x16x32_bf16 v[82:85], v[14:17], v[124:127], v[8:11]
	s_mov_b32 s3, 0x18000
	s_nop 1
	v_lshlrev_b64 v[8:9], 10, v[58:59]
	v_min_i32_e32 v10, 0x401f, v74
	v_lshl_add_u64 v[8:9], v[172:173], 0, v[8:9]
	v_ashrrev_i32_e32 v11, 31, v10
	v_mfma_f32_16x16x32_bf16 v[26:29], v[78:81], v[242:245], v[94:97]
	v_add_co_u32_e32 v8, vcc, s10, v8
	v_lshlrev_b64 v[10:11], 10, v[10:11]
	v_mfma_f32_16x16x32_bf16 v[90:93], v[14:17], v[46:49], v[66:69]
	v_addc_co_u32_e32 v9, vcc, 0, v9, vcc
	v_lshl_add_u64 v[10:11], v[172:173], 0, v[10:11]
	v_mfma_f32_16x16x32_bf16 v[86:89], v[14:17], v[18:21], v[70:73]
	v_add_co_u32_e32 v10, vcc, s3, v10
	s_waitcnt lgkmcnt(1)
	v_mfma_f32_16x16x32_bf16 v[78:81], v[22:25], v[168:171], v[140:143]
	v_addc_co_u32_e32 v11, vcc, 0, v11, vcc
	v_mfma_f32_16x16x32_bf16 v[74:77], v[22:25], v[46:49], v[144:147]
	v_mfma_f32_16x16x32_bf16 v[70:73], v[22:25], v[18:21], v[148:151]
	v_mfma_f32_16x16x32_bf16 v[66:69], v[22:25], v[124:127], v[152:155]
	v_lshlrev_b64 v[22:23], 10, v[184:185]
	v_lshl_add_u64 v[22:23], s[6:7], 0, v[22:23]
	v_lshl_add_u64 v[22:23], v[22:23], 0, s[12:13]
	v_lshl_add_u64 v[22:23], v[22:23], 0, v[116:117]
	v_add_co_u32_e32 v140, vcc, s10, v22
	v_mfma_f32_16x16x32_bf16 v[94:97], v[14:17], v[168:171], v[62:65]
	global_load_dwordx4 v[14:17], v[8:9], off
	s_nop 0
	global_load_dwordx4 v[8:11], v[10:11], off
	v_addc_co_u32_e32 v141, vcc, 0, v23, vcc
	s_waitcnt lgkmcnt(0)
	v_mfma_f32_16x16x32_bf16 v[58:61], v[180:183], v[46:49], v[160:163]
	v_mfma_f32_16x16x32_bf16 v[46:49], v[180:183], v[18:21], v[26:29]
	global_load_dwordx4 v[22:25], v[22:23], off
	s_nop 0
	global_load_dwordx4 v[18:21], v[140:141], off
	v_mfma_f32_16x16x32_bf16 v[62:65], v[180:183], v[168:171], v[156:159]
	v_mfma_f32_16x16x32_bf16 v[26:29], v[180:183], v[124:127], v[176:179]
	s_cbranch_scc1 .LBB0_722
	ds_read2_b32 v[126:127], v138 offset1:16
	ds_read2_b32 v[124:125], v138 offset0:32 offset1:48
	s_cmpk_gt_i32 s34, 0x2ff
	s_mov_b64 s[12:13], -1
	s_cbranch_scc0 .LBB0_731
	s_add_i32 s10, s34, 0xfffffd00
	s_movk_i32 s11, 0x4000
	s_cbranch_execz .LBB0_732

;     ...
;     auto compute = [&](int buf) {
;       const unsigned char* Ab = As + buf * ASTG + (wn * 64 + lr) * 128;
;       const unsigned char* Ax = Ax0 + buf * 128;
;       const unsigned char* Bb = Bs + buf * 16384 + (wm * 64 + lr) * 128;
; #pragma unroll
;       for (int ks = 0; ks < 2; ++ks) {
;         if (TI == 5 && ks == 1) __builtin_amdgcn_sched_barrier(0);
;         const int sw = ((ks * 4 + lq) ^ (lr & 7)) << 4;
;         bf16x8 wf[4], xf[TI];
; #pragma unroll
;         for (int i = 0; i < 4; ++i) {
;           wf[i] = *(const bf16x8*)(Bb + i * 2048 + sw);
;           xf[i] = *(const bf16x8*)(Ab + i * 2048 + sw);
;         }
.LBB0_746:
	v_add_u32_e32 v121, v139, v140
	ds_read_b128 v[26:29], v121 offset:32768
	v_add_u32_e32 v126, v138, v140
	ds_read_b128 v[30:33], v126
	ds_read_b128 v[34:37], v121 offset:34816
	ds_read_b128 v[38:41], v126 offset:2048
	ds_read_b128 v[242:245], v126 offset:4096
	ds_read_b128 v[246:249], v126 offset:6144
	ds_read_b128 v[250:253], v121 offset:36864
	s_min_i32 s10, s7, s13
	s_cmpk_gt_i32 s10, 0x3ff
	s_mov_b64 s[4:5], -1
	s_cbranch_scc0 .LBB0_748
	s_add_i32 s8, s10, 0xfffffc00
	s_mov_b64 s[4:5], 0

; #define MFMA16(a, b, c) __builtin_amdgcn_mfma_f32_16x16x32_bf16((a), (b), (c), 0, 0, 0)
; __device__ __forceinline__ void rem_tile(int pos, int& mt, int& nt) { if (pos < 65) { mt = pos; nt = 40; } else { mt = 64; nt = pos - 65; } }
;     ...
;     auto issue = [&](u32x4 (&ra)[4], u32x4 (&rb)[2], u32x4& rx) {
;       const int idc = l_id < last_id ? l_id : last_id;
;       int mt, nt; if (TMAP == 1) rem_tile(idc, mt, nt); else tile_of(idc, ntn, mt, nt);
;       const bf16_t* A = (l_kt < ktsplit) ? A0 : A1;
;       const int kk = (l_kt < ktsplit) ? l_kt : l_kt - ktsplit;
;       const int arow = mt * 2 * BMH + hh * BMH + srow;
;       const bf16_t* akb = A + kk * kstride + (tid & 7) * 8;
;       const bf16_t* wp = W + (size_t)(nt * 128 + wrow) * K + l_kt * 64 + (tid5 & 7) * 8;
; #pragma unroll
;       for (int i = 0; i < 4; ++i) {
;         int r = arow + 32 * i; r = r < M_ ? r : M_ - 1;
;         ra[i] = *(const u32x4*)(akb + (size_t)r * lda);
;       }
; #pragma unroll
;       for (int i = 0; i < 2; ++i) rb[i] = *(const u32x4*)(wp + (size_t)i * 64 * K);
;     ...
;     auto compute = [&](int buf) {
;       const unsigned char* Ab = As + buf * ASTG + (wn * 64 + lr) * 128;
;       const unsigned char* Ax = Ax0 + buf * 128;
;       const unsigned char* Bb = Bs + buf * 16384 + (wm * 64 + lr) * 128;
; #pragma unroll
;       for (int ks = 0; ks < 2; ++ks) {
;         if (TI == 5 && ks == 1) __builtin_amdgcn_sched_barrier(0);
;         const int sw = ((ks * 4 + lq) ^ (lr & 7)) << 4;
;         bf16x8 wf[4], xf[TI];
; #pragma unroll
;         for (int i = 0; i < 4; ++i) {
;           wf[i] = *(const bf16x8*)(Bb + i * 2048 + sw);
;           xf[i] = *(const bf16x8*)(Ab + i * 2048 + sw);
;         }
;         if (TI == 5) xf[TI - 1] = *(const bf16x8*)(Ax + ((ks * 4 + lq) << 4));
; #pragma unroll
;         for (int ni = 0; ni < 4; ++ni)
; #pragma unroll
;           for (int ti = 0; ti < 4; ++ti) acc[ni][ti] = MFMA16(wf[ni], xf[ti], acc[ni][ti]);
;         if (TI == 5) {
;           if (wn == 0) { acc[0][TI - 1] = MFMA16(wf[0], xf[TI - 1], acc[0][TI - 1]); acc[1][TI - 1] = MFMA16(wf[1], xf[TI - 1], acc[1][TI - 1]); }
;           else { acc[2][TI - 1] = MFMA16(wf[2], xf[TI - 1], acc[2][TI - 1]); acc[3][TI - 1] = MFMA16(wf[3], xf[TI - 1], acc[3][TI - 1]); }
;         }
;       }
;     };
.LBB0_750:
	s_cmp_lt_i32 s6, 2.0
	s_cselect_b32 s11, s43, 0
	s_waitcnt lgkmcnt(3)
	v_mfma_f32_16x16x32_bf16 v[94:97], v[34:37], v[38:41], v[94:97]
	s_cselect_b32 s10, s42, 0
	v_add_u32_e32 v117, s4, v135
	s_lshl_b32 s4, s6, 6
	v_mfma_f32_16x16x32_bf16 v[42:45], v[26:29], v[30:33], v[110:113]
	s_ashr_i32 s5, s4, 31
	s_lshl_b64 s[4:5], s[4:5], 1
	v_add_u32_e32 v13, v139, v141
	v_mfma_f32_16x16x32_bf16 v[46:49], v[26:29], v[38:41], v[102:105]
	s_nop 2
	s_add_u32 s10, s10, s4
	s_addc_u32 s11, s11, s5
	s_waitcnt lgkmcnt(2)
	v_mfma_f32_16x16x32_bf16 v[86:89], v[26:29], v[242:245], v[86:89]
	v_mov_b32_e32 v115, v12
	v_lshl_add_u64 v[132:133], s[10:11], 0, v[114:115]
	s_movk_i32 s3, 0x4000
	s_waitcnt lgkmcnt(1)
	v_mfma_f32_16x16x32_bf16 v[26:29], v[26:29], v[246:249], v[70:73]
	v_add_u32_e32 v127, v138, v141
	v_lshl_add_u32 v162, s8, 7, v134
	v_ashrrev_i32_e32 v163, 31, v162
	v_mfma_f32_16x16x32_bf16 v[70:73], v[34:37], v[30:33], v[106:109]
	s_mov_b32 s8, 0xc000
	s_add_i32 s9, s9, 1
	s_cmp_lg_u32 s9, 4
	v_mfma_f32_16x16x32_bf16 v[78:81], v[34:37], v[242:245], v[78:81]
	v_mfma_f32_16x16x32_bf16 v[128:131], v[34:37], v[246:249], v[62:65]
	ds_read_b128 v[34:37], v121 offset:38912
	s_nop 1
	v_min_i32_e32 v62, 0x407f, v117
	v_ashrrev_i32_e32 v63, 31, v62
	s_waitcnt lgkmcnt(1)
	v_mfma_f32_16x16x32_bf16 v[98:101], v[250:253], v[30:33], v[98:101]
	v_mfma_f32_16x16x32_bf16 v[146:149], v[250:253], v[38:41], v[82:85]
	v_mfma_f32_16x16x32_bf16 v[150:153], v[250:253], v[242:245], v[66:69]
	v_mfma_f32_16x16x32_bf16 v[106:109], v[250:253], v[246:249], v[54:57]
	s_nop 2
	v_lshlrev_b64 v[54:55], 9, v[62:63]
	ds_read_b128 v[62:65], v13 offset:32768
	s_waitcnt lgkmcnt(1)
	v_mfma_f32_16x16x32_bf16 v[154:157], v[34:37], v[30:33], v[90:93]
	v_min_i32_e32 v30, 0x405f, v117
	v_ashrrev_i32_e32 v31, 31, v30
	v_lshlrev_b64 v[30:31], 9, v[30:31]
	v_lshl_add_u64 v[30:31], v[132:133], 0, v[30:31]
	v_add_co_u32_e32 v30, vcc, s3, v30
	v_lshl_add_u64 v[54:55], v[132:133], 0, v[54:55]
	s_nop 0
	v_addc_co_u32_e32 v31, vcc, 0, v31, vcc
	v_mfma_f32_16x16x32_bf16 v[158:161], v[34:37], v[38:41], v[74:77]
	s_mov_b32 s3, 0x8000
	v_mfma_f32_16x16x32_bf16 v[168:171], v[34:37], v[242:245], v[58:61]
	ds_read_b128 v[102:105], v127
	global_load_dwordx4 v[38:41], v[54:55], off
	s_nop 0
	global_load_dwordx4 v[30:33], v[30:31], off
	ds_read_b128 v[82:85], v13 offset:34816
	ds_read_b128 v[180:183], v127 offset:2048
	ds_read_b128 v[202:205], v127 offset:4096
	ds_read_b128 v[206:209], v127 offset:6144
	v_mfma_f32_16x16x32_bf16 v[176:179], v[34:37], v[246:249], v[50:53]
	v_min_i32_e32 v34, 0x403f, v117
	v_ashrrev_i32_e32 v35, 31, v34
	v_lshlrev_b64 v[34:35], 9, v[34:35]
	v_min_i32_e32 v36, 0x401f, v117
	v_lshl_add_u64 v[34:35], v[132:133], 0, v[34:35]
	v_ashrrev_i32_e32 v37, 31, v36
	s_waitcnt lgkmcnt(4)
	v_mfma_f32_16x16x32_bf16 v[50:53], v[62:65], v[102:105], v[42:45]
	v_add_co_u32_e32 v34, vcc, s3, v34
	v_mov_b32_e32 v117, v12
	s_waitcnt lgkmcnt(2)
	v_mfma_f32_16x16x32_bf16 v[54:57], v[62:65], v[180:183], v[46:49]
	v_lshlrev_b64 v[42:43], 9, v[162:163]
	v_addc_co_u32_e32 v35, vcc, 0, v35, vcc
	s_waitcnt lgkmcnt(1)
	v_mfma_f32_16x16x32_bf16 v[58:61], v[62:65], v[202:205], v[86:89]
	v_lshl_add_u64 v[42:43], s[44:45], 0, v[42:43]
	v_lshl_add_u64 v[42:43], v[42:43], 0, s[4:5]
	v_lshl_add_u64 v[42:43], v[42:43], 0, v[116:117]
	s_waitcnt lgkmcnt(0)
	v_mfma_f32_16x16x32_bf16 v[62:65], v[62:65], v[206:209], v[26:29]
	s_waitcnt vmcnt(7)
	v_and_b32_e32 v111, 0xffff0000, v4
	s_waitcnt vmcnt(6)
	v_and_b32_e32 v110, 0xffff0000, v0
	v_lshlrev_b64 v[26:27], 9, v[36:37]
	v_lshl_add_u64 v[26:27], v[132:133], 0, v[26:27]
	v_add_co_u32_e32 v26, vcc, s8, v26
	v_mfma_f32_16x16x32_bf16 v[66:69], v[82:85], v[102:105], v[70:73]
	s_nop 0
	v_addc_co_u32_e32 v27, vcc, 0, v27, vcc
	v_add_co_u32_e32 v44, vcc, s3, v42
	global_load_dwordx4 v[34:37], v[34:35], off
	s_nop 0
	global_load_dwordx4 v[26:29], v[26:27], off
	v_addc_co_u32_e32 v45, vcc, 0, v43, vcc
	v_mfma_f32_16x16x32_bf16 v[70:73], v[82:85], v[180:183], v[94:97]
	v_mul_f32_e64 v132, v110, v110
	v_mul_f32_e64 v133, v111, v111
	v_mfma_f32_16x16x32_bf16 v[74:77], v[82:85], v[202:205], v[78:81]
	ds_read_b128 v[94:97], v13 offset:36864
	v_mfma_f32_16x16x32_bf16 v[78:81], v[82:85], v[206:209], v[128:131]
	s_nop 2
	ds_read_b128 v[128:131], v13 offset:38912
	global_load_dwordx4 v[46:49], v[42:43], off
	s_nop 0
	global_load_dwordx4 v[42:45], v[44:45], off
	s_waitcnt lgkmcnt(1)
; #define MFMA16(a, b, c) __builtin_amdgcn_mfma_f32_16x16x32_bf16((a), (b), (c), 0, 0, 0)
;     ...
;     auto store = [&](const u32x4 (&ra)[4], const u32x4 (&rb)[2], const u32x4& rx, int buf) {
; #pragma unroll
;       for (int i = 0; i < 4; ++i) {
;         if (RS) ss[i] += sumsq8(__builtin_bit_cast(bf16x8, ra[i]));
;         *(u32x4*)(As + buf * ASTG + i * 4096 + soff) = ra[i];
;       }
; #pragma unroll
;       for (int i = 0; i < 2; ++i) *(u32x4*)(Bs + buf * 16384 + i * 8192 + woff) = rb[i];
;       if (TI == 5) {
;         if (RS) ss[4] += sumsq8(__builtin_bit_cast(bf16x8, rx));
;         if (srow == 0) *(u32x4*)(Ax0 + buf * 128 + ((tid & 7) << 4)) = rx;
;       }
;       if (RS) {
;         if (++st_kt == nk) {
;           st_kt = 0;
; #pragma unroll
;           for (int i = 0; i < TI; ++i) {
;             float t = ss[i];
;             t += __shfl_xor(t, 1); t += __shfl_xor(t, 2); t += __shfl_xor(t, 4);
;             if ((tid & 7) == 0 && i < 4) rsl[srow + 32 * i] = rsqrtf(t * invK + EPS_);
;             ss[i] = 0.f;
;           }
;         }
;       }
;     };
;     auto compute = [&](int buf) {
;       const unsigned char* Ab = As + buf * ASTG + (wn * 64 + lr) * 128;
;       const unsigned char* Ax = Ax0 + buf * 128;
;       const unsigned char* Bb = Bs + buf * 16384 + (wm * 64 + lr) * 128;
; #pragma unroll
;       for (int ks = 0; ks < 2; ++ks) {
;         if (TI == 5 && ks == 1) __builtin_amdgcn_sched_barrier(0);
;         const int sw = ((ks * 4 + lq) ^ (lr & 7)) << 4;
;         bf16x8 wf[4], xf[TI];
; #pragma unroll
;         for (int i = 0; i < 4; ++i) {
;           wf[i] = *(const bf16x8*)(Bb + i * 2048 + sw);
;           xf[i] = *(const bf16x8*)(Ab + i * 2048 + sw);
;         }
;         if (TI == 5) xf[TI - 1] = *(const bf16x8*)(Ax + ((ks * 4 + lq) << 4));
; #pragma unroll
;         for (int ni = 0; ni < 4; ++ni)
; #pragma unroll
;           for (int ti = 0; ti < 4; ++ti) acc[ni][ti] = MFMA16(wf[ni], xf[ti], acc[ni][ti]);
;         if (TI == 5) {
;           if (wn == 0) { acc[0][TI - 1] = MFMA16(wf[0], xf[TI - 1], acc[0][TI - 1]); acc[1][TI - 1] = MFMA16(wf[1], xf[TI - 1], acc[1][TI - 1]); }
;           else { acc[2][TI - 1] = MFMA16(wf[2], xf[TI - 1], acc[2][TI - 1]); acc[3][TI - 1] = MFMA16(wf[3], xf[TI - 1], acc[3][TI - 1]); }
;         }
;       }
;     };
	v_mfma_f32_16x16x32_bf16 v[82:85], v[94:97], v[102:105], v[98:101]
	ds_write_b128 v137, v[4:7] offset:16384
	ds_write_b128 v137, v[0:3] offset:20480
	s_waitcnt vmcnt(9)
	ds_write_b128 v137, v[14:17] offset:24576
	v_lshlrev_b32_e32 v101, 16, v4
	v_lshlrev_b32_e32 v100, 16, v0
	v_and_b32_e32 v99, 0xffff0000, v5
	v_mfma_f32_16x16x32_bf16 v[86:89], v[94:97], v[180:183], v[146:149]
	v_lshlrev_b32_e32 v5, 16, v5
	v_lshlrev_b32_e32 v4, 16, v1
	v_and_b32_e32 v98, 0xffff0000, v1
	v_mfma_f32_16x16x32_bf16 v[90:93], v[94:97], v[202:205], v[150:153]
	v_and_b32_e32 v1, 0xffff0000, v15
	s_waitcnt vmcnt(8)
	v_and_b32_e32 v0, 0xffff0000, v9
	ds_write_b128 v137, v[8:11] offset:28672
	s_waitcnt vmcnt(7)
	ds_write_b128 v136, v[22:25] offset:49152
	v_mfma_f32_16x16x32_bf16 v[110:113], v[94:97], v[206:209], v[106:109]
	v_fma_f32 v94, v100, v100, v132
	v_fma_f32 v95, v101, v101, v133
	s_waitcnt vmcnt(6)
	ds_write_b128 v136, v[18:21] offset:57344
	v_pk_fma_f32 v[4:5], v[4:5], v[4:5], v[94:95]
	v_lshlrev_b32_e32 v95, 16, v6
	v_pk_fma_f32 v[4:5], v[98:99], v[98:99], v[4:5]
	v_lshlrev_b32_e32 v94, 16, v2
	v_pk_fma_f32 v[4:5], v[94:95], v[94:95], v[4:5]
	v_and_b32_e32 v99, 0xffff0000, v6
	v_and_b32_e32 v98, 0xffff0000, v2
	s_waitcnt lgkmcnt(6)
	v_mfma_f32_16x16x32_bf16 v[102:105], v[128:131], v[102:105], v[154:157]
	v_fma_f32 v4, v98, v98, v4
	v_fma_f32 v5, v99, v99, v5
	v_and_b32_e32 v6, 0xffff0000, v3
	v_lshlrev_b32_e32 v2, 16, v8
	v_mfma_f32_16x16x32_bf16 v[106:109], v[128:131], v[180:183], v[158:161]
	v_mfma_f32_16x16x32_bf16 v[94:97], v[128:131], v[202:205], v[168:171]
	v_mfma_f32_16x16x32_bf16 v[98:101], v[128:131], v[206:209], v[176:179]
	v_lshlrev_b32_e32 v129, 16, v7
	v_lshlrev_b32_e32 v128, 16, v3
	v_pk_fma_f32 v[4:5], v[128:129], v[128:129], v[4:5]
	v_and_b32_e32 v7, 0xffff0000, v7
	v_pk_fma_f32 v[4:5], v[6:7], v[6:7], v[4:5]
	v_lshlrev_b32_e32 v3, 16, v14
	v_pk_add_f32 v[124:125], v[124:125], v[4:5]
	v_and_b32_e32 v5, 0xffff0000, v14
	v_and_b32_e32 v4, 0xffff0000, v8
	v_pk_mul_f32 v[4:5], v[4:5], v[4:5]
	v_lshlrev_b32_e32 v7, 16, v15
	v_lshlrev_b32_e32 v6, 16, v9
	v_pk_fma_f32 v[2:3], v[2:3], v[2:3], v[4:5]
	s_nop 0
	v_pk_fma_f32 v[2:3], v[6:7], v[6:7], v[2:3]
	s_nop 0
	v_pk_fma_f32 v[0:1], v[0:1], v[0:1], v[2:3]
	v_lshlrev_b32_e32 v3, 16, v16
	v_lshlrev_b32_e32 v2, 16, v10
	v_pk_fma_f32 v[0:1], v[2:3], v[2:3], v[0:1]
	v_and_b32_e32 v3, 0xffff0000, v16
	v_and_b32_e32 v2, 0xffff0000, v10
	v_pk_fma_f32 v[0:1], v[2:3], v[2:3], v[0:1]
	v_lshlrev_b32_e32 v3, 16, v17
	v_lshlrev_b32_e32 v2, 16, v11
	v_pk_fma_f32 v[0:1], v[2:3], v[2:3], v[0:1]
	v_and_b32_e32 v3, 0xffff0000, v17
	v_and_b32_e32 v2, 0xffff0000, v11
	v_pk_fma_f32 v[0:1], v[2:3], v[2:3], v[0:1]
	s_nop 0
	v_pk_add_f32 v[122:123], v[122:123], v[0:1]
	s_cbranch_scc1 .LBB0_760
	v_and_b32_e32 v1, 64, v191
	v_xor_b32_e32 v0, 1, v191
	v_add_u32_e32 v2, 64, v1
	v_cmp_lt_i32_e32 vcc, v0, v2
	v_xor_b32_e32 v1, 2, v191
	v_xor_b32_e32 v5, 4, v191
	v_cndmask_b32_e32 v0, v191, v0, vcc
	v_lshlrev_b32_e32 v0, 2, v0
	ds_bpermute_b32 v3, v0, v125
	v_cmp_lt_i32_e32 vcc, v1, v2
	s_waitcnt lgkmcnt(0)
	v_add_f32_e32 v3, v125, v3
	v_cndmask_b32_e32 v1, v191, v1, vcc
	v_lshlrev_b32_e32 v1, 2, v1
	ds_bpermute_b32 v4, v1, v3
	v_cmp_lt_i32_e32 vcc, v5, v2
	s_waitcnt lgkmcnt(0)
	v_add_f32_e32 v3, v3, v4
	v_cndmask_b32_e32 v2, v191, v5, vcc
	v_lshlrev_b32_e32 v2, 2, v2
	ds_bpermute_b32 v4, v2, v3
	s_and_saveexec_b64 s[4:5], s[38:39]
	s_cbranch_execz .LBB0_753
	s_waitcnt lgkmcnt(0)
	v_add_f32_e32 v3, v3, v4
	v_fmamk_f32 v3, v3, 0x3b800000, v187
	v_mul_f32_e32 v4, 0x4b800000, v3
	v_cmp_gt_f32_e32 vcc, s33, v3
	s_nop 1
	v_cndmask_b32_e32 v3, v3, v4, vcc
	v_rsq_f32_e32 v3, v3
	s_nop 0
	v_mul_f32_e32 v4, 0x45800000, v3
	v_cndmask_b32_e32 v3, v3, v4, vcc
	ds_write_b32 v142, v3

;     ...
;     auto compute = [&](int buf) {
;       const unsigned char* Ab = As + buf * ASTG + (wn * 64 + lr) * 128;
;       const unsigned char* Ax = Ax0 + buf * 128;
;       const unsigned char* Bb = Bs + buf * 16384 + (wm * 64 + lr) * 128;
; #pragma unroll
;       for (int ks = 0; ks < 2; ++ks) {
;         if (TI == 5 && ks == 1) __builtin_amdgcn_sched_barrier(0);
;         const int sw = ((ks * 4 + lq) ^ (lr & 7)) << 4;
;         bf16x8 wf[4], xf[TI];
; #pragma unroll
;         for (int i = 0; i < 4; ++i) {
;           wf[i] = *(const bf16x8*)(Bb + i * 2048 + sw);
;           xf[i] = *(const bf16x8*)(Ab + i * 2048 + sw);
;         }
.LBB0_760:
	s_add_i32 s11, s6, 1
	s_cmp_eq_u32 s11, 4
	s_cselect_b64 s[4:5], -1, 0
	s_and_b64 s[36:37], s[4:5], exec
	s_load_dwordx2 s[36:37], s[0:1], 0x110
	s_waitcnt lgkmcnt(0)
	s_barrier
	ds_read_b128 v[0:3], v121 offset:49152
	ds_read_b128 v[4:7], v126 offset:16384
	ds_read_b128 v[8:11], v121 offset:51200
	ds_read_b128 v[14:17], v126 offset:18432
	ds_read_b128 v[242:245], v126 offset:20480
	ds_read_b128 v[246:249], v126 offset:22528
	ds_read_b128 v[250:253], v121 offset:53248
	s_cselect_b32 s8, s36, 0
	s_add_i32 s8, s8, s7
	s_min_i32 s36, s8, s13
	s_cmpk_gt_i32 s36, 0x3ff
	s_mov_b64 s[6:7], -1
	s_cbranch_scc0 .LBB0_762
	s_add_i32 s10, s36, 0xfffffc00
	s_mov_b64 s[6:7], 0

; #define MFMA16(a, b, c) __builtin_amdgcn_mfma_f32_16x16x32_bf16((a), (b), (c), 0, 0, 0)
; __device__ __forceinline__ void rem_tile(int pos, int& mt, int& nt) { if (pos < 65) { mt = pos; nt = 40; } else { mt = 64; nt = pos - 65; } }
;     ...
;     auto issue = [&](u32x4 (&ra)[4], u32x4 (&rb)[2], u32x4& rx) {
;       const int idc = l_id < last_id ? l_id : last_id;
;       int mt, nt; if (TMAP == 1) rem_tile(idc, mt, nt); else tile_of(idc, ntn, mt, nt);
;       const bf16_t* A = (l_kt < ktsplit) ? A0 : A1;
;       const int kk = (l_kt < ktsplit) ? l_kt : l_kt - ktsplit;
;       const int arow = mt * 2 * BMH + hh * BMH + srow;
;       const bf16_t* akb = A + kk * kstride + (tid & 7) * 8;
;       const bf16_t* wp = W + (size_t)(nt * 128 + wrow) * K + l_kt * 64 + (tid5 & 7) * 8;
; #pragma unroll
;       for (int i = 0; i < 4; ++i) {
;         int r = arow + 32 * i; r = r < M_ ? r : M_ - 1;
;         ra[i] = *(const u32x4*)(akb + (size_t)r * lda);
;       }
; #pragma unroll
;       for (int i = 0; i < 2; ++i) rb[i] = *(const u32x4*)(wp + (size_t)i * 64 * K);
;     ...
;     auto compute = [&](int buf) {
;       const unsigned char* Ab = As + buf * ASTG + (wn * 64 + lr) * 128;
;       const unsigned char* Ax = Ax0 + buf * 128;
;       const unsigned char* Bb = Bs + buf * 16384 + (wm * 64 + lr) * 128;
; #pragma unroll
;       for (int ks = 0; ks < 2; ++ks) {
;         if (TI == 5 && ks == 1) __builtin_amdgcn_sched_barrier(0);
;         const int sw = ((ks * 4 + lq) ^ (lr & 7)) << 4;
;         bf16x8 wf[4], xf[TI];
; #pragma unroll
;         for (int i = 0; i < 4; ++i) {
;           wf[i] = *(const bf16x8*)(Bb + i * 2048 + sw);
;           xf[i] = *(const bf16x8*)(Ab + i * 2048 + sw);
;         }
;         if (TI == 5) xf[TI - 1] = *(const bf16x8*)(Ax + ((ks * 4 + lq) << 4));
; #pragma unroll
;         for (int ni = 0; ni < 4; ++ni)
; #pragma unroll
;           for (int ti = 0; ti < 4; ++ti) acc[ni][ti] = MFMA16(wf[ni], xf[ti], acc[ni][ti]);
;         if (TI == 5) {
;           if (wn == 0) { acc[0][TI - 1] = MFMA16(wf[0], xf[TI - 1], acc[0][TI - 1]); acc[1][TI - 1] = MFMA16(wf[1], xf[TI - 1], acc[1][TI - 1]); }
;           else { acc[2][TI - 1] = MFMA16(wf[2], xf[TI - 1], acc[2][TI - 1]); acc[3][TI - 1] = MFMA16(wf[3], xf[TI - 1], acc[3][TI - 1]); }
;         }
;       }
;     };
.LBB0_764:
	s_and_b64 s[4:5], s[4:5], exec
	s_cselect_b32 s6, 0, s11
	s_waitcnt lgkmcnt(5)
	v_mfma_f32_16x16x32_bf16 v[18:21], v[0:3], v[4:7], v[50:53]
	s_cmp_lt_i32 s6, 2.0
	s_cselect_b32 s11, s43, 0
	s_cselect_b32 s36, s42, 0
	s_waitcnt lgkmcnt(3)
	v_mfma_f32_16x16x32_bf16 v[22:25], v[0:3], v[14:17], v[54:57]
	s_nop 1
	s_lshl_b32 s4, s6, 6
	v_add_u32_e32 v117, s7, v135
	s_waitcnt lgkmcnt(2)
	v_mfma_f32_16x16x32_bf16 v[58:61], v[0:3], v[242:245], v[58:61]
	s_ashr_i32 s5, s4, 31
	s_lshl_b64 s[4:5], s[4:5], 1
	s_add_u32 s36, s36, s4
	s_waitcnt lgkmcnt(1)
	v_mfma_f32_16x16x32_bf16 v[0:3], v[0:3], v[246:249], v[62:65]
	s_addc_u32 s37, s11, s5
	v_mov_b32_e32 v115, v12
	s_movk_i32 s3, 0x4000
	v_mfma_f32_16x16x32_bf16 v[62:65], v[8:11], v[4:7], v[66:69]
	v_lshl_add_u32 v126, s10, 7, v134
	s_mov_b32 s7, 0xc000
	s_add_i32 s35, s35, 2
	v_mfma_f32_16x16x32_bf16 v[66:69], v[8:11], v[14:17], v[70:73]
	s_cmp_lg_u32 s35, 4
	v_mfma_f32_16x16x32_bf16 v[74:77], v[8:11], v[242:245], v[74:77]
	v_mfma_f32_16x16x32_bf16 v[8:11], v[8:11], v[246:249], v[78:81]
	s_nop 1
	ds_read_b128 v[78:81], v121 offset:55296
	ds_read_b128 v[158:161], v127 offset:16384
	s_waitcnt lgkmcnt(2)
	v_mfma_f32_16x16x32_bf16 v[82:85], v[250:253], v[4:7], v[82:85]
	s_waitcnt lgkmcnt(1)
	v_mfma_f32_16x16x32_bf16 v[150:153], v[78:81], v[4:7], v[102:105]
	ds_read_b128 v[4:7], v13 offset:49152
	v_mfma_f32_16x16x32_bf16 v[128:131], v[250:253], v[14:17], v[86:89]
	v_mfma_f32_16x16x32_bf16 v[154:157], v[78:81], v[14:17], v[106:109]
	ds_read_b128 v[14:17], v13 offset:51200
	ds_read_b128 v[176:179], v127 offset:18432
	ds_read_b128 v[180:183], v127 offset:22528
	s_waitcnt lgkmcnt(1)
	v_mfma_f32_16x16x32_bf16 v[102:105], v[4:7], v[176:179], v[22:25]
	s_nop 2
	v_min_i32_e32 v22, 0x407f, v117
	v_ashrrev_i32_e32 v23, 31, v22
	v_mfma_f32_16x16x32_bf16 v[90:93], v[250:253], v[242:245], v[90:93]
	v_mfma_f32_16x16x32_bf16 v[146:149], v[250:253], v[246:249], v[110:113]
	s_waitcnt lgkmcnt(0)
	v_mfma_f32_16x16x32_bf16 v[70:73], v[4:7], v[180:183], v[0:3]
	s_nop 2
	v_min_i32_e32 v2, 0x405f, v117
	v_mfma_f32_16x16x32_bf16 v[110:113], v[4:7], v[158:161], v[18:21]
	v_lshlrev_b64 v[0:1], 9, v[22:23]
	v_ashrrev_i32_e32 v3, 31, v2
	ds_read_b128 v[22:25], v13 offset:53248
	ds_read_b128 v[18:21], v127 offset:20480
	v_mfma_f32_16x16x32_bf16 v[168:171], v[78:81], v[246:249], v[98:101]
	v_lshl_add_u64 v[54:55], s[36:37], 0, v[114:115]
	v_lshlrev_b64 v[2:3], 9, v[2:3]
	v_lshl_add_u64 v[2:3], v[54:55], 0, v[2:3]
	v_add_co_u32_e32 v2, vcc, s3, v2
	v_lshl_add_u64 v[0:1], v[54:55], 0, v[0:1]
	s_nop 0
	v_addc_co_u32_e32 v3, vcc, 0, v3, vcc
	s_waitcnt lgkmcnt(0)
	v_mfma_f32_16x16x32_bf16 v[86:89], v[4:7], v[18:21], v[58:61]
	global_load_dwordx4 v[4:7], v[0:1], off
	s_nop 0
	global_load_dwordx4 v[0:3], v[2:3], off
	v_min_i32_e32 v56, 0x403f, v117
	ds_read_b128 v[202:205], v13 offset:55296
	v_mfma_f32_16x16x32_bf16 v[106:109], v[14:17], v[158:161], v[62:65]
	v_ashrrev_i32_e32 v57, 31, v56
	v_ashrrev_i32_e32 v127, 31, v126
	s_mov_b32 s3, 0x8000
	v_mfma_f32_16x16x32_bf16 v[62:65], v[14:17], v[180:183], v[8:11]
	s_nop 2
	v_min_i32_e32 v10, 0x401f, v117
	v_lshlrev_b64 v[8:9], 9, v[56:57]
	v_ashrrev_i32_e32 v11, 31, v10
	v_lshl_add_u64 v[8:9], v[54:55], 0, v[8:9]
	v_lshlrev_b64 v[10:11], 9, v[10:11]
	v_mfma_f32_16x16x32_bf16 v[50:53], v[78:81], v[242:245], v[94:97]
	v_add_co_u32_e32 v8, vcc, s3, v8
	v_lshl_add_u64 v[10:11], v[54:55], 0, v[10:11]
	v_mfma_f32_16x16x32_bf16 v[94:97], v[14:17], v[176:179], v[66:69]
	v_addc_co_u32_e32 v9, vcc, 0, v9, vcc
	v_add_co_u32_e32 v10, vcc, s7, v10
	v_mfma_f32_16x16x32_bf16 v[98:101], v[22:25], v[158:161], v[82:85]
	v_mov_b32_e32 v117, v12
	v_addc_co_u32_e32 v11, vcc, 0, v11, vcc
	v_mfma_f32_16x16x32_bf16 v[82:85], v[22:25], v[176:179], v[128:131]
	v_mfma_f32_16x16x32_bf16 v[66:69], v[22:25], v[18:21], v[90:93]
	v_mfma_f32_16x16x32_bf16 v[54:57], v[22:25], v[180:183], v[146:149]
	v_lshlrev_b64 v[22:23], 9, v[126:127]
	v_lshl_add_u64 v[22:23], s[44:45], 0, v[22:23]
	v_lshl_add_u64 v[22:23], v[22:23], 0, s[4:5]
	v_lshl_add_u64 v[22:23], v[22:23], 0, v[116:117]
	v_add_co_u32_e32 v126, vcc, s3, v22
	v_mfma_f32_16x16x32_bf16 v[78:81], v[14:17], v[18:21], v[74:77]
	global_load_dwordx4 v[14:17], v[8:9], off
	s_nop 0
	global_load_dwordx4 v[8:11], v[10:11], off
	v_addc_co_u32_e32 v127, vcc, 0, v23, vcc
	s_waitcnt lgkmcnt(0)
	v_mfma_f32_16x16x32_bf16 v[58:61], v[202:205], v[18:21], v[50:53]
	global_load_dwordx4 v[22:25], v[22:23], off
	s_nop 0
	global_load_dwordx4 v[18:21], v[126:127], off
	v_mfma_f32_16x16x32_bf16 v[90:93], v[202:205], v[158:161], v[150:153]
	v_mfma_f32_16x16x32_bf16 v[74:77], v[202:205], v[176:179], v[154:157]
	v_mfma_f32_16x16x32_bf16 v[50:53], v[202:205], v[180:183], v[168:171]
	s_cbranch_scc1 .LBB0_776
	ds_read2_b32 v[128:129], v144 offset1:16
	ds_read2_b32 v[126:127], v144 offset0:32 offset1:48
	s_cmpk_gt_i32 s12, 0x3ff
	s_mov_b64 s[4:5], -1
	s_cbranch_scc0 .LBB0_768
	s_add_i32 s7, s12, 0xfffffc00
	s_movk_i32 s4, 0x4000
	s_cbranch_execz .LBB0_769
